# phase 3 conformer-conv tile: early full wait before the 120 row loads of a channel pass removed (no pending destination is touched before the later wait); the tile's flat loads (global pointers) issue
# speedup vs baseline: 1.0046x; 1.0040x over previous
.LBB0_451:
	v_lshlrev_b32_e32 v52, 16, v52
	v_lshlrev_b32_e32 v54, 16, v54
	v_cndmask_b32_e64 v52, v52, 0, s[16:17]
	v_lshlrev_b32_e32 v56, 16, v56
	v_cndmask_b32_e64 v54, v54, 0, s[16:17]
	v_mul_f32_e32 v52, 0xbfb8aa3b, v52
	v_lshlrev_b32_e32 v58, 16, v58
	v_cndmask_b32_e64 v56, v56, 0, s[16:17]
	v_mul_f32_e32 v54, 0xbfb8aa3b, v54
	v_exp_f32_e32 v52, v52
	v_lshlrev_b32_e32 v60, 16, v60
	v_cndmask_b32_e64 v58, v58, 0, s[16:17]
	v_mul_f32_e32 v56, 0xbfb8aa3b, v56
	v_exp_f32_e32 v54, v54
	v_lshlrev_b32_e32 v62, 16, v62
	v_cndmask_b32_e64 v60, v60, 0, s[16:17]
	v_mul_f32_e32 v58, 0xbfb8aa3b, v58
	v_exp_f32_e32 v56, v56
	v_lshlrev_b32_e32 v64, 16, v64
	v_cndmask_b32_e64 v62, v62, 0, s[16:17]
	v_mul_f32_e32 v60, 0xbfb8aa3b, v60
	v_exp_f32_e32 v58, v58
	v_lshlrev_b32_e32 v66, 16, v66
	v_cndmask_b32_e64 v64, v64, 0, s[16:17]
	v_mul_f32_e32 v62, 0xbfb8aa3b, v62
	v_exp_f32_e32 v60, v60
	v_add_f32_e32 v52, 1.0, v52
	v_lshlrev_b32_e32 v69, 16, v69
	v_cndmask_b32_e64 v66, v66, 0, s[16:17]
	v_mul_f32_e32 v64, 0xbfb8aa3b, v64
	v_exp_f32_e32 v62, v62
	v_add_f32_e32 v54, 1.0, v54
	v_rcp_f32_e32 v52, v52
	v_lshlrev_b32_e32 v74, 16, v74
	v_cndmask_b32_e64 v69, v69, 0, s[16:17]
	v_mul_f32_e32 v66, 0xbfb8aa3b, v66
	v_exp_f32_e32 v64, v64
	v_add_f32_e32 v56, 1.0, v56
	v_rcp_f32_e32 v54, v54
	v_lshlrev_b32_e32 v80, 16, v80
	v_cndmask_b32_e64 v74, v74, 0, s[16:17]
	v_mul_f32_e32 v69, 0xbfb8aa3b, v69
	v_exp_f32_e32 v66, v66
	v_add_f32_e32 v58, 1.0, v58
	v_rcp_f32_e32 v56, v56
	v_lshlrev_b32_e32 v51, 16, v51
	v_lshlrev_b32_e32 v84, 16, v84
	v_cndmask_b32_e64 v80, v80, 0, s[16:17]
	v_mul_f32_e32 v74, 0xbfb8aa3b, v74
	v_exp_f32_e32 v69, v69
	v_add_f32_e32 v60, 1.0, v60
	v_rcp_f32_e32 v58, v58
	v_lshlrev_b32_e32 v53, 16, v53
	v_cndmask_b32_e64 v51, v51, 0, s[16:17]
	v_lshlrev_b32_e32 v89, 16, v89
	v_cndmask_b32_e64 v84, v84, 0, s[16:17]
	v_mul_f32_e32 v80, 0xbfb8aa3b, v80
	v_exp_f32_e32 v74, v74
	v_add_f32_e32 v62, 1.0, v62
	v_rcp_f32_e32 v60, v60
	v_lshlrev_b32_e32 v55, 16, v55
	v_cndmask_b32_e64 v53, v53, 0, s[16:17]
	v_mul_f32_e32 v51, v52, v51
	v_lshlrev_b32_e32 v94, 16, v94
	v_cndmask_b32_e64 v89, v89, 0, s[16:17]
	v_mul_f32_e32 v84, 0xbfb8aa3b, v84
	v_exp_f32_e32 v80, v80
	v_add_f32_e32 v64, 1.0, v64
	v_rcp_f32_e32 v62, v62
	v_lshlrev_b32_e32 v57, 16, v57
	v_cndmask_b32_e64 v55, v55, 0, s[16:17]
	v_mul_f32_e32 v53, v54, v53
	s_waitcnt lgkmcnt(0)
	v_fma_f32 v52, v7, v51, 0
	v_lshlrev_b32_e32 v100, 16, v100
	v_cndmask_b32_e64 v94, v94, 0, s[16:17]
	v_mul_f32_e32 v89, 0xbfb8aa3b, v89
	v_exp_f32_e32 v84, v84
	v_add_f32_e32 v66, 1.0, v66
	v_rcp_f32_e32 v64, v64
	v_lshlrev_b32_e32 v59, 16, v59
	v_cndmask_b32_e64 v57, v57, 0, s[16:17]
	v_mul_f32_e32 v55, v56, v55
	v_fma_f32 v54, v7, v53, 0
	v_fmac_f32_e32 v52, v5, v53
	v_lshlrev_b32_e32 v105, 16, v105
	v_cndmask_b32_e64 v100, v100, 0, s[16:17]
	v_mul_f32_e32 v94, 0xbfb8aa3b, v94
	v_exp_f32_e32 v89, v89
	v_add_f32_e32 v69, 1.0, v69
	v_rcp_f32_e32 v66, v66
	v_lshlrev_b32_e32 v61, 16, v61
	v_cndmask_b32_e64 v59, v59, 0, s[16:17]
	v_mul_f32_e32 v58, v58, v57
	v_fma_f32 v56, v7, v55, 0
	v_fmac_f32_e32 v54, v5, v55
	v_fmac_f32_e32 v52, v8, v55
	v_lshlrev_b32_e32 v110, 16, v110
	v_cndmask_b32_e64 v105, v105, 0, s[16:17]
	v_mul_f32_e32 v100, 0xbfb8aa3b, v100
	v_exp_f32_e32 v94, v94
	v_add_f32_e32 v74, 1.0, v74
	v_rcp_f32_e32 v69, v69
	v_lshlrev_b32_e32 v63, 16, v63
	v_cndmask_b32_e64 v61, v61, 0, s[16:17]
	v_mul_f32_e32 v60, v60, v59
	v_fma_f32 v57, v7, v58, 0
	v_fmac_f32_e32 v56, v5, v58
	v_fmac_f32_e32 v54, v8, v58
	v_fmac_f32_e32 v52, v6, v58
	v_lshlrev_b32_e32 v114, 16, v114
	v_cndmask_b32_e64 v110, v110, 0, s[16:17]
	v_mul_f32_e32 v105, 0xbfb8aa3b, v105
	v_exp_f32_e32 v100, v100
	v_add_f32_e32 v80, 1.0, v80
	v_rcp_f32_e32 v74, v74
	v_lshlrev_b32_e32 v65, 16, v65
	v_cndmask_b32_e64 v63, v63, 0, s[16:17]
	v_mul_f32_e32 v62, v62, v61
	v_fma_f32 v59, v7, v60, 0
	v_fmac_f32_e32 v57, v5, v60
	v_fmac_f32_e32 v56, v8, v60
	v_fmac_f32_e32 v54, v6, v60
	v_fmac_f32_e32 v52, v10, v60
	v_lshlrev_b32_e32 v118, 16, v118
	v_cndmask_b32_e64 v114, v114, 0, s[16:17]
	v_mul_f32_e32 v110, 0xbfb8aa3b, v110
	v_exp_f32_e32 v105, v105
	v_add_f32_e32 v84, 1.0, v84
	v_rcp_f32_e32 v80, v80
	v_lshlrev_b32_e32 v68, 16, v68
	v_cndmask_b32_e64 v65, v65, 0, s[16:17]
	v_mul_f32_e32 v64, v64, v63
	v_fma_f32 v61, v7, v62, 0
	v_fmac_f32_e32 v59, v5, v62
	v_fmac_f32_e32 v57, v8, v62
	v_fmac_f32_e32 v56, v6, v62
	v_fmac_f32_e32 v54, v10, v62
	v_fmac_f32_e32 v52, v9, v62
	v_lshlrev_b32_e32 v119, 16, v119
	v_cndmask_b32_e64 v118, v118, 0, s[16:17]
	v_mul_f32_e32 v114, 0xbfb8aa3b, v114
	v_exp_f32_e32 v110, v110
	v_add_f32_e32 v89, 1.0, v89
	v_rcp_f32_e32 v84, v84
	v_lshlrev_b32_e32 v73, 16, v73
	v_cndmask_b32_e64 v68, v68, 0, s[16:17]
	v_mul_f32_e32 v66, v66, v65
	v_fma_f32 v63, v7, v64, 0
	v_fmac_f32_e32 v61, v5, v64
	v_fmac_f32_e32 v59, v8, v64
	v_fmac_f32_e32 v57, v6, v64
	v_fmac_f32_e32 v56, v10, v64
	v_fmac_f32_e32 v54, v9, v64
	v_fmac_f32_e32 v52, v15, v64
	v_lshlrev_b32_e32 v116, 16, v116
	v_cndmask_b32_e64 v119, v119, 0, s[16:17]
	v_mul_f32_e32 v118, 0xbfb8aa3b, v118
	v_exp_f32_e32 v114, v114
	v_add_f32_e32 v94, 1.0, v94
	v_rcp_f32_e32 v89, v89
	v_lshlrev_b32_e32 v79, 16, v79
	v_cndmask_b32_e64 v73, v73, 0, s[16:17]
	v_mul_f32_e32 v69, v69, v68
	v_fma_f32 v65, v7, v66, 0
	v_fmac_f32_e32 v63, v5, v66
	v_fmac_f32_e32 v61, v8, v66
	v_fmac_f32_e32 v59, v6, v66
	v_fmac_f32_e32 v57, v10, v66
	v_fmac_f32_e32 v56, v9, v66
	v_fmac_f32_e32 v54, v15, v66
	v_fmac_f32_e32 v52, v12, v66
	v_lshlrev_b32_e32 v111, 16, v111
	v_cndmask_b32_e64 v116, v116, 0, s[16:17]
	v_mul_f32_e32 v119, 0xbfb8aa3b, v119
	v_exp_f32_e32 v118, v118
	v_add_f32_e32 v100, 1.0, v100
	v_rcp_f32_e32 v94, v94
	v_lshlrev_b32_e32 v83, 16, v83
	v_cndmask_b32_e64 v79, v79, 0, s[16:17]
	v_mul_f32_e32 v74, v74, v73
	v_fma_f32 v68, v7, v69, 0
	v_fmac_f32_e32 v65, v5, v69
	v_fmac_f32_e32 v63, v8, v69
	v_fmac_f32_e32 v61, v6, v69
	v_fmac_f32_e32 v59, v10, v69
	v_fmac_f32_e32 v57, v9, v69
	v_fmac_f32_e32 v56, v15, v69
	v_fmac_f32_e32 v54, v12, v69
	v_fmac_f32_e32 v52, v13, v69
	v_lshlrev_b32_e32 v106, 16, v106
	v_cndmask_b32_e64 v111, v111, 0, s[16:17]
	v_mul_f32_e32 v116, 0xbfb8aa3b, v116
	v_exp_f32_e32 v119, v119
	v_add_f32_e32 v105, 1.0, v105
	v_rcp_f32_e32 v100, v100
	v_lshlrev_b32_e32 v88, 16, v88
	v_cndmask_b32_e64 v83, v83, 0, s[16:17]
	v_mul_f32_e32 v80, v80, v79
	v_fma_f32 v73, v7, v74, 0
	v_fmac_f32_e32 v68, v5, v74
	v_fmac_f32_e32 v65, v8, v74
	v_fmac_f32_e32 v63, v6, v74
	v_fmac_f32_e32 v61, v10, v74
	v_fmac_f32_e32 v59, v9, v74
	v_fmac_f32_e32 v57, v15, v74
	v_fmac_f32_e32 v56, v12, v74
	v_fmac_f32_e32 v54, v13, v74
	v_fmac_f32_e32 v52, v11, v74
	v_lshlrev_b32_e32 v101, 16, v101
	v_cndmask_b32_e64 v106, v106, 0, s[16:17]
	v_mul_f32_e32 v111, 0xbfb8aa3b, v111
	v_exp_f32_e32 v116, v116
	v_add_f32_e32 v110, 1.0, v110
	v_rcp_f32_e32 v105, v105
	v_lshlrev_b32_e32 v93, 16, v93
	v_cndmask_b32_e64 v88, v88, 0, s[16:17]
	v_mul_f32_e32 v84, v84, v83
	v_fma_f32 v79, v7, v80, 0
	v_fmac_f32_e32 v73, v5, v80
	v_fmac_f32_e32 v68, v8, v80
	v_fmac_f32_e32 v65, v6, v80
	v_fmac_f32_e32 v63, v10, v80
	v_fmac_f32_e32 v61, v9, v80
	v_fmac_f32_e32 v59, v15, v80
	v_fmac_f32_e32 v57, v12, v80
	v_fmac_f32_e32 v56, v13, v80
	v_fmac_f32_e32 v54, v11, v80
	v_fmac_f32_e32 v52, v16, v80
	v_lshlrev_b32_e32 v96, 16, v96
	v_cndmask_b32_e64 v101, v101, 0, s[16:17]
	v_mul_f32_e32 v106, 0xbfb8aa3b, v106
	v_exp_f32_e32 v111, v111
	v_add_f32_e32 v114, 1.0, v114
	v_rcp_f32_e32 v110, v110
	v_lshlrev_b32_e32 v98, 16, v98
	v_cndmask_b32_e64 v93, v93, 0, s[16:17]
	v_mul_f32_e32 v89, v89, v88
	v_fma_f32 v83, v7, v84, 0
	v_fmac_f32_e32 v79, v5, v84
	v_fmac_f32_e32 v73, v8, v84
	v_fmac_f32_e32 v68, v6, v84
	v_fmac_f32_e32 v65, v10, v84
	v_fmac_f32_e32 v63, v9, v84
	v_fmac_f32_e32 v61, v15, v84
	v_fmac_f32_e32 v59, v12, v84
	v_fmac_f32_e32 v57, v13, v84
	v_fmac_f32_e32 v56, v11, v84
	v_fmac_f32_e32 v54, v16, v84
	v_fmac_f32_e32 v52, v14, v84
	v_lshlrev_b32_e32 v91, 16, v91
	v_cndmask_b32_e64 v96, v96, 0, s[16:17]
	v_mul_f32_e32 v101, 0xbfb8aa3b, v101
	v_exp_f32_e32 v106, v106
	v_add_f32_e32 v118, 1.0, v118
	v_rcp_f32_e32 v114, v114
	v_lshlrev_b32_e32 v102, 16, v102
	v_cndmask_b32_e64 v98, v98, 0, s[16:17]
	v_mul_f32_e32 v94, v94, v93
	v_fma_f32 v88, v7, v89, 0
	v_fmac_f32_e32 v83, v5, v89
	v_fmac_f32_e32 v79, v8, v89
	v_fmac_f32_e32 v73, v6, v89
	v_fmac_f32_e32 v68, v10, v89
	v_fmac_f32_e32 v65, v9, v89
	v_fmac_f32_e32 v63, v15, v89
	v_fmac_f32_e32 v61, v12, v89
	v_fmac_f32_e32 v59, v13, v89
	v_fmac_f32_e32 v57, v11, v89
	v_fmac_f32_e32 v56, v16, v89
	v_fmac_f32_e32 v54, v14, v89
	v_fmac_f32_e32 v52, v23, v89
	v_lshlrev_b32_e32 v86, 16, v86
	v_cndmask_b32_e64 v91, v91, 0, s[16:17]
	v_mul_f32_e32 v96, 0xbfb8aa3b, v96
	v_exp_f32_e32 v101, v101
	v_add_f32_e32 v119, 1.0, v119
	v_rcp_f32_e32 v118, v118
	v_lshlrev_b32_e32 v108, 16, v108
	v_cndmask_b32_e64 v102, v102, 0, s[16:17]
	v_mul_f32_e32 v100, v100, v98
	v_fma_f32 v93, v7, v94, 0
	v_fmac_f32_e32 v88, v5, v94
	v_fmac_f32_e32 v83, v8, v94
	v_fmac_f32_e32 v79, v6, v94
	v_fmac_f32_e32 v73, v10, v94
	v_fmac_f32_e32 v68, v9, v94
	v_fmac_f32_e32 v65, v15, v94
	v_fmac_f32_e32 v63, v12, v94
	v_fmac_f32_e32 v61, v13, v94
	v_fmac_f32_e32 v59, v11, v94
	v_fmac_f32_e32 v57, v16, v94
	v_fmac_f32_e32 v56, v14, v94
	v_fmac_f32_e32 v54, v23, v94
	v_fmac_f32_e32 v52, v17, v94
	v_cndmask_b32_e64 v86, v86, 0, s[16:17]
	v_mul_f32_e32 v91, 0xbfb8aa3b, v91
	v_exp_f32_e32 v96, v96
	v_add_f32_e32 v116, 1.0, v116
	v_rcp_f32_e32 v119, v119
	v_lshlrev_b32_e32 v113, 16, v113
	v_cndmask_b32_e64 v108, v108, 0, s[16:17]
	v_mul_f32_e32 v105, v105, v102
	v_fma_f32 v98, v7, v100, 0
	v_fmac_f32_e32 v93, v5, v100
	v_fmac_f32_e32 v88, v8, v100
	v_fmac_f32_e32 v83, v6, v100
	v_fmac_f32_e32 v79, v10, v100
	v_fmac_f32_e32 v73, v9, v100
	v_fmac_f32_e32 v68, v15, v100
	v_fmac_f32_e32 v65, v12, v100
	v_fmac_f32_e32 v63, v13, v100
	v_fmac_f32_e32 v61, v11, v100
	v_fmac_f32_e32 v59, v16, v100
	v_fmac_f32_e32 v57, v14, v100
	v_fmac_f32_e32 v56, v23, v100
	v_fmac_f32_e32 v54, v17, v100
	v_fmac_f32_e32 v52, v32, v100
	v_lshlrev_b32_e32 v72, 16, v72
	v_mul_f32_e32 v86, 0xbfb8aa3b, v86
	v_exp_f32_e32 v91, v91
	v_add_f32_e32 v111, 1.0, v111
	v_rcp_f32_e32 v116, v116
	v_lshlrev_b32_e32 v117, 16, v117
	v_cndmask_b32_e64 v113, v113, 0, s[16:17]
	v_mul_f32_e32 v110, v110, v108
	v_fma_f32 v102, v7, v105, 0
	v_fmac_f32_e32 v98, v5, v105
	v_fmac_f32_e32 v93, v8, v105
	v_fmac_f32_e32 v88, v6, v105
	v_fmac_f32_e32 v83, v10, v105
	v_fmac_f32_e32 v79, v9, v105
	v_fmac_f32_e32 v73, v15, v105
	v_fmac_f32_e32 v68, v12, v105
	v_fmac_f32_e32 v65, v13, v105
	v_fmac_f32_e32 v63, v11, v105
	v_fmac_f32_e32 v61, v16, v105
	v_fmac_f32_e32 v59, v14, v105
	v_fmac_f32_e32 v57, v23, v105
	v_fmac_f32_e32 v56, v17, v105
	v_fmac_f32_e32 v54, v32, v105
	v_fmac_f32_e32 v52, v25, v105
	v_mul_f32_e32 v72, 0xbfb8aa3b, v72
	v_lshlrev_b32_e32 v77, 16, v77
	v_exp_f32_e32 v86, v86
	v_add_f32_e32 v106, 1.0, v106
	v_rcp_f32_e32 v111, v111
	v_lshlrev_b32_e32 v112, 16, v112
	v_cndmask_b32_e64 v117, v117, 0, s[16:17]
	v_mul_f32_e32 v114, v114, v113
	v_fma_f32 v108, v7, v110, 0
	v_fmac_f32_e32 v102, v5, v110
	v_fmac_f32_e32 v98, v8, v110
	v_fmac_f32_e32 v93, v6, v110
	v_fmac_f32_e32 v88, v10, v110
	v_fmac_f32_e32 v83, v9, v110
	v_fmac_f32_e32 v79, v15, v110
	v_fmac_f32_e32 v73, v12, v110
	v_fmac_f32_e32 v68, v13, v110
	v_fmac_f32_e32 v65, v11, v110
	v_fmac_f32_e32 v63, v16, v110
	v_fmac_f32_e32 v61, v14, v110
	v_fmac_f32_e32 v59, v23, v110
	v_fmac_f32_e32 v57, v17, v110
	v_fmac_f32_e32 v56, v32, v110
	v_fmac_f32_e32 v54, v25, v110
	v_fmac_f32_e32 v52, v26, v110
	v_exp_f32_e32 v72, v72
	v_mul_f32_e32 v77, 0xbfb8aa3b, v77
	v_add_f32_e32 v101, 1.0, v101
	v_rcp_f32_e32 v106, v106
	v_lshlrev_b32_e32 v107, 16, v107
	v_cndmask_b32_e64 v112, v112, 0, s[16:17]
	v_mul_f32_e32 v118, v118, v117
	v_fma_f32 v113, v7, v114, 0
	v_fmac_f32_e32 v108, v5, v114
	v_fmac_f32_e32 v102, v8, v114
	v_fmac_f32_e32 v98, v6, v114
	v_fmac_f32_e32 v93, v10, v114
	v_fmac_f32_e32 v88, v9, v114
	v_fmac_f32_e32 v83, v15, v114
	v_fmac_f32_e32 v79, v12, v114
	v_fmac_f32_e32 v73, v13, v114
	v_fmac_f32_e32 v68, v11, v114
	v_fmac_f32_e32 v65, v16, v114
	v_fmac_f32_e32 v63, v14, v114
	v_fmac_f32_e32 v61, v23, v114
	v_fmac_f32_e32 v59, v17, v114
	v_fmac_f32_e32 v57, v32, v114
	v_fmac_f32_e32 v56, v25, v114
	v_fmac_f32_e32 v54, v26, v114
	v_fmac_f32_e32 v52, v24, v114
	v_exp_f32_e32 v77, v77
	v_add_f32_e32 v96, 1.0, v96
	v_rcp_f32_e32 v101, v101
	v_lshlrev_b32_e32 v104, 16, v104
	v_cndmask_b32_e64 v107, v107, 0, s[16:17]
	v_mul_f32_e32 v119, v119, v112
	v_fma_f32 v117, v7, v118, 0
	v_fmac_f32_e32 v113, v5, v118
	v_fmac_f32_e32 v108, v8, v118
	v_fmac_f32_e32 v102, v6, v118
	v_fmac_f32_e32 v98, v10, v118
	v_fmac_f32_e32 v93, v9, v118
	v_fmac_f32_e32 v88, v15, v118
	v_fmac_f32_e32 v83, v12, v118
	v_fmac_f32_e32 v79, v13, v118
	v_fmac_f32_e32 v73, v11, v118
	v_fmac_f32_e32 v68, v16, v118
	v_fmac_f32_e32 v65, v14, v118
	v_fmac_f32_e32 v63, v23, v118
	v_fmac_f32_e32 v61, v17, v118
	v_fmac_f32_e32 v59, v32, v118
	v_fmac_f32_e32 v57, v25, v118
	v_fmac_f32_e32 v56, v26, v118
	v_fmac_f32_e32 v54, v24, v118
	v_fmac_f32_e32 v52, v33, v118
	v_add_f32_e32 v91, 1.0, v91
	v_rcp_f32_e32 v96, v96
	v_lshlrev_b32_e32 v99, 16, v99
	v_cndmask_b32_e64 v104, v104, 0, s[16:17]
	v_mul_f32_e32 v116, v116, v107
	v_fma_f32 v112, v7, v119, 0
	v_fmac_f32_e32 v117, v5, v119
	v_fmac_f32_e32 v113, v8, v119
	v_fmac_f32_e32 v108, v6, v119
	v_fmac_f32_e32 v102, v10, v119
	v_fmac_f32_e32 v98, v9, v119
	v_fmac_f32_e32 v93, v15, v119
	v_fmac_f32_e32 v88, v12, v119
	v_fmac_f32_e32 v83, v13, v119
	v_fmac_f32_e32 v79, v11, v119
	v_fmac_f32_e32 v73, v16, v119
	v_fmac_f32_e32 v68, v14, v119
	v_fmac_f32_e32 v65, v23, v119
	v_fmac_f32_e32 v63, v17, v119
	v_fmac_f32_e32 v61, v32, v119
	v_fmac_f32_e32 v59, v25, v119
	v_fmac_f32_e32 v57, v26, v119
	v_fmac_f32_e32 v56, v24, v119
	v_fmac_f32_e32 v54, v33, v119
	v_fmac_f32_e32 v52, v27, v119
	v_add_f32_e32 v86, 1.0, v86
	v_rcp_f32_e32 v91, v91
	v_lshlrev_b32_e32 v95, 16, v95
	v_cndmask_b32_e64 v99, v99, 0, s[16:17]
	v_mul_f32_e32 v111, v111, v104
	v_fma_f32 v107, v7, v116, 0
	v_fmac_f32_e32 v112, v5, v116
	v_fmac_f32_e32 v117, v8, v116
	v_fmac_f32_e32 v113, v6, v116
	v_fmac_f32_e32 v108, v10, v116
	v_fmac_f32_e32 v102, v9, v116
	v_fmac_f32_e32 v98, v15, v116
	v_fmac_f32_e32 v93, v12, v116
	v_fmac_f32_e32 v88, v13, v116
	v_fmac_f32_e32 v83, v11, v116
	v_fmac_f32_e32 v79, v16, v116
	v_fmac_f32_e32 v73, v14, v116
	v_fmac_f32_e32 v68, v23, v116
	v_fmac_f32_e32 v65, v17, v116
	v_fmac_f32_e32 v63, v32, v116
	v_fmac_f32_e32 v61, v25, v116
	v_fmac_f32_e32 v59, v26, v116
	v_fmac_f32_e32 v57, v24, v116
	v_fmac_f32_e32 v56, v33, v116
	v_fmac_f32_e32 v54, v27, v116
	v_fmac_f32_e32 v52, v35, v116
	v_lshlrev_b32_e32 v50, 16, v50
	v_add_f32_e32 v72, 1.0, v72
	v_rcp_f32_e32 v86, v86
	v_lshlrev_b32_e32 v90, 16, v90
	v_cndmask_b32_e64 v95, v95, 0, s[16:17]
	v_mul_f32_e32 v106, v106, v99
	v_fma_f32 v104, v7, v111, 0
	v_fmac_f32_e32 v107, v5, v111
	v_fmac_f32_e32 v112, v8, v111
	v_fmac_f32_e32 v117, v6, v111
	v_fmac_f32_e32 v113, v10, v111
	v_fmac_f32_e32 v108, v9, v111
	v_fmac_f32_e32 v102, v15, v111
	v_fmac_f32_e32 v98, v12, v111
	v_fmac_f32_e32 v93, v13, v111
	v_fmac_f32_e32 v88, v11, v111
	v_fmac_f32_e32 v83, v16, v111
	v_fmac_f32_e32 v79, v14, v111
	v_fmac_f32_e32 v73, v23, v111
	v_fmac_f32_e32 v68, v17, v111
	v_fmac_f32_e32 v65, v32, v111
	v_fmac_f32_e32 v63, v25, v111
	v_fmac_f32_e32 v61, v26, v111
	v_fmac_f32_e32 v59, v24, v111
	v_fmac_f32_e32 v57, v33, v111
	v_fmac_f32_e32 v56, v27, v111
	v_fmac_f32_e32 v54, v35, v111
	v_fmac_f32_e32 v52, v34, v111
	v_cndmask_b32_e64 v50, v50, 0, s[16:17]
	v_rcp_f32_e32 v72, v72
	v_add_f32_e32 v77, 1.0, v77
	v_lshlrev_b32_e32 v85, 16, v85
	v_cndmask_b32_e64 v90, v90, 0, s[16:17]
	v_mul_f32_e32 v101, v101, v95
	v_fma_f32 v99, v7, v106, 0
	v_fmac_f32_e32 v104, v5, v106
	v_fmac_f32_e32 v107, v8, v106
	v_fmac_f32_e32 v112, v6, v106
	v_fmac_f32_e32 v117, v10, v106
	v_fmac_f32_e32 v113, v9, v106
	v_fmac_f32_e32 v108, v15, v106
	v_fmac_f32_e32 v102, v12, v106
	v_fmac_f32_e32 v98, v13, v106
	v_fmac_f32_e32 v93, v11, v106
	v_fmac_f32_e32 v88, v16, v106
	v_fmac_f32_e32 v83, v14, v106
	v_fmac_f32_e32 v79, v23, v106
	v_fmac_f32_e32 v73, v17, v106
	v_fmac_f32_e32 v68, v32, v106
	v_fmac_f32_e32 v65, v25, v106
	v_fmac_f32_e32 v63, v26, v106
	v_fmac_f32_e32 v61, v24, v106
	v_fmac_f32_e32 v59, v33, v106
	v_fmac_f32_e32 v57, v27, v106
	v_fmac_f32_e32 v56, v35, v106
	v_fmac_f32_e32 v54, v34, v106
	v_fmac_f32_e32 v52, v40, v106
	v_mul_f32_e32 v50, 0xbfb8aa3b, v50
	v_rcp_f32_e32 v133, v77
	v_lshlrev_b32_e32 v81, 16, v81
	v_cndmask_b32_e64 v85, v85, 0, s[16:17]
	v_mul_f32_e32 v96, v96, v90
	v_fma_f32 v95, v7, v101, 0
	v_fmac_f32_e32 v99, v5, v101
	v_fmac_f32_e32 v104, v8, v101
	v_fmac_f32_e32 v107, v6, v101
	v_fmac_f32_e32 v112, v10, v101
	v_fmac_f32_e32 v117, v9, v101
	v_fmac_f32_e32 v113, v15, v101
	v_fmac_f32_e32 v108, v12, v101
	v_fmac_f32_e32 v102, v13, v101
	v_fmac_f32_e32 v98, v11, v101
	v_fmac_f32_e32 v93, v16, v101
	v_fmac_f32_e32 v88, v14, v101
	v_fmac_f32_e32 v83, v23, v101
	v_fmac_f32_e32 v79, v17, v101
	v_fmac_f32_e32 v73, v32, v101
	v_fmac_f32_e32 v68, v25, v101
	v_fmac_f32_e32 v65, v26, v101
	v_fmac_f32_e32 v63, v24, v101
	v_fmac_f32_e32 v61, v33, v101
	v_fmac_f32_e32 v59, v27, v101
	v_fmac_f32_e32 v57, v35, v101
	v_fmac_f32_e32 v56, v34, v101
	v_fmac_f32_e32 v54, v40, v101
	v_fmac_f32_e32 v52, v37, v101
	v_exp_f32_e32 v50, v50
	v_cndmask_b32_e64 v81, v81, 0, s[16:17]
	v_mul_f32_e32 v91, v91, v85
	v_fma_f32 v90, v7, v96, 0
	v_fmac_f32_e32 v95, v5, v96
	v_fmac_f32_e32 v99, v8, v96
	v_fmac_f32_e32 v104, v6, v96
	v_fmac_f32_e32 v107, v10, v96
	v_fmac_f32_e32 v112, v9, v96
	v_fmac_f32_e32 v117, v15, v96
	v_fmac_f32_e32 v113, v12, v96
	v_fmac_f32_e32 v108, v13, v96
	v_fmac_f32_e32 v102, v11, v96
	v_fmac_f32_e32 v98, v16, v96
	v_fmac_f32_e32 v93, v14, v96
	v_fmac_f32_e32 v88, v23, v96
	v_fmac_f32_e32 v83, v17, v96
	v_fmac_f32_e32 v79, v32, v96
	v_fmac_f32_e32 v73, v25, v96
	v_fmac_f32_e32 v68, v26, v96
	v_fmac_f32_e32 v65, v24, v96
	v_fmac_f32_e32 v63, v33, v96
	v_fmac_f32_e32 v61, v27, v96
	v_fmac_f32_e32 v59, v35, v96
	v_fmac_f32_e32 v57, v34, v96
	v_fmac_f32_e32 v56, v40, v96
	v_fmac_f32_e32 v54, v37, v96
	v_fmac_f32_e32 v52, v38, v96
	v_lshlrev_b32_e32 v71, 16, v71
	v_mul_f32_e32 v86, v86, v81
	v_fma_f32 v85, v7, v91, 0
	v_fmac_f32_e32 v90, v5, v91
	v_fmac_f32_e32 v95, v8, v91
	v_fmac_f32_e32 v99, v6, v91
	v_fmac_f32_e32 v104, v10, v91
	v_fmac_f32_e32 v107, v9, v91
	v_fmac_f32_e32 v112, v15, v91
	v_fmac_f32_e32 v117, v12, v91
	v_fmac_f32_e32 v113, v13, v91
	v_fmac_f32_e32 v108, v11, v91
	v_fmac_f32_e32 v102, v16, v91
	v_fmac_f32_e32 v98, v14, v91
	v_fmac_f32_e32 v93, v23, v91
	v_fmac_f32_e32 v88, v17, v91
	v_fmac_f32_e32 v83, v32, v91
	v_fmac_f32_e32 v79, v25, v91
	v_fmac_f32_e32 v73, v26, v91
	v_fmac_f32_e32 v68, v24, v91
	v_fmac_f32_e32 v65, v33, v91
	v_fmac_f32_e32 v63, v27, v91
	v_fmac_f32_e32 v61, v35, v91
	v_fmac_f32_e32 v59, v34, v91
	v_fmac_f32_e32 v57, v40, v91
	v_fmac_f32_e32 v56, v37, v91
	v_fmac_f32_e32 v54, v38, v91
	v_fmac_f32_e32 v52, v36, v91
	v_mul_f32_e32 v77, v72, v71
	v_lshlrev_b32_e32 v72, 16, v78
	v_fma_f32 v81, v7, v86, 0
	v_fmac_f32_e32 v85, v5, v86
	v_fmac_f32_e32 v90, v8, v86
	v_fmac_f32_e32 v95, v6, v86
	v_fmac_f32_e32 v99, v10, v86
	v_fmac_f32_e32 v104, v9, v86
	v_fmac_f32_e32 v107, v15, v86
	v_fmac_f32_e32 v112, v12, v86
	v_fmac_f32_e32 v117, v13, v86
	v_fmac_f32_e32 v113, v11, v86
	v_fmac_f32_e32 v108, v16, v86
	v_fmac_f32_e32 v102, v14, v86
	v_fmac_f32_e32 v98, v23, v86
	v_fmac_f32_e32 v93, v17, v86
	v_fmac_f32_e32 v88, v32, v86
	v_fmac_f32_e32 v83, v25, v86
	v_fmac_f32_e32 v79, v26, v86
	v_fmac_f32_e32 v73, v24, v86
	v_fmac_f32_e32 v68, v33, v86
	v_fmac_f32_e32 v65, v27, v86
	v_fmac_f32_e32 v63, v35, v86
	v_fmac_f32_e32 v61, v34, v86
	v_fmac_f32_e32 v59, v40, v86
	v_fmac_f32_e32 v57, v37, v86
	v_fmac_f32_e32 v56, v38, v86
	v_fmac_f32_e32 v54, v36, v86
	v_fmac_f32_e32 v52, v41, v86
	v_fma_f32 v71, v7, v77, 0
	v_mul_f32_e32 v78, v133, v72
	v_fmac_f32_e32 v81, v5, v77
	v_fmac_f32_e32 v85, v8, v77
	v_fmac_f32_e32 v90, v6, v77
	v_fmac_f32_e32 v95, v10, v77
	v_fmac_f32_e32 v99, v9, v77
	v_fmac_f32_e32 v104, v15, v77
	v_fmac_f32_e32 v107, v12, v77
	v_fmac_f32_e32 v112, v13, v77
	v_fmac_f32_e32 v117, v11, v77
	v_fmac_f32_e32 v113, v16, v77
	v_fmac_f32_e32 v108, v14, v77
	v_fmac_f32_e32 v102, v23, v77
	v_fmac_f32_e32 v98, v17, v77
	v_fmac_f32_e32 v93, v32, v77
	v_fmac_f32_e32 v88, v25, v77
	v_fmac_f32_e32 v83, v26, v77
	v_fmac_f32_e32 v79, v24, v77
	v_fmac_f32_e32 v73, v33, v77
	v_fmac_f32_e32 v68, v27, v77
	v_fmac_f32_e32 v65, v35, v77
	v_fmac_f32_e32 v63, v34, v77
	v_fmac_f32_e32 v61, v40, v77
	v_fmac_f32_e32 v59, v37, v77
	v_fmac_f32_e32 v57, v38, v77
	v_fmac_f32_e32 v56, v36, v77
	v_fmac_f32_e32 v54, v41, v77
	v_fmac_f32_e32 v52, v39, v77
	v_add_f32_e32 v50, 1.0, v50
	v_fmac_f32_e32 v71, v5, v78
	v_fma_f32 v72, v7, v78, 0
	v_fmac_f32_e32 v81, v8, v78
	v_fmac_f32_e32 v85, v6, v78
	v_fmac_f32_e32 v90, v10, v78
	v_fmac_f32_e32 v95, v9, v78
	v_fmac_f32_e32 v99, v15, v78
	v_fmac_f32_e32 v104, v12, v78
	v_fmac_f32_e32 v107, v13, v78
	v_fmac_f32_e32 v112, v11, v78
	v_fmac_f32_e32 v117, v16, v78
	v_fmac_f32_e32 v113, v14, v78
	v_fmac_f32_e32 v108, v23, v78
	v_fmac_f32_e32 v102, v17, v78
	v_fmac_f32_e32 v98, v32, v78
	v_fmac_f32_e32 v93, v25, v78
	v_fmac_f32_e32 v88, v26, v78
	v_fmac_f32_e32 v83, v24, v78
	v_fmac_f32_e32 v79, v33, v78
	v_fmac_f32_e32 v73, v27, v78
	v_fmac_f32_e32 v68, v35, v78
	v_fmac_f32_e32 v65, v34, v78
	v_fmac_f32_e32 v63, v40, v78
	v_fmac_f32_e32 v61, v37, v78
	v_fmac_f32_e32 v59, v38, v78
	v_fmac_f32_e32 v57, v36, v78
	v_fmac_f32_e32 v56, v41, v78
	v_fmac_f32_e32 v54, v39, v78
	v_fmac_f32_e32 v52, v43, v78
	v_rcp_f32_e32 v50, v50
	v_fmac_f32_e32 v71, v8, v2
	v_fmac_f32_e32 v72, v5, v2
	v_fmac_f32_e32 v81, v6, v2
	v_fmac_f32_e32 v85, v10, v2
	v_fmac_f32_e32 v90, v9, v2
	v_fmac_f32_e32 v95, v15, v2
	v_fmac_f32_e32 v99, v12, v2
	v_fmac_f32_e32 v104, v13, v2
	v_fmac_f32_e32 v107, v11, v2
	v_fmac_f32_e32 v112, v16, v2
	v_fmac_f32_e32 v117, v14, v2
	v_fmac_f32_e32 v113, v23, v2
	v_fmac_f32_e32 v108, v17, v2
	v_fmac_f32_e32 v102, v32, v2
	v_fmac_f32_e32 v98, v25, v2
	v_fmac_f32_e32 v93, v26, v2
	v_fmac_f32_e32 v88, v24, v2
	v_fmac_f32_e32 v83, v33, v2
	v_fmac_f32_e32 v79, v27, v2
	v_fmac_f32_e32 v73, v35, v2
	v_fmac_f32_e32 v68, v34, v2
	v_fmac_f32_e32 v65, v40, v2
	v_fmac_f32_e32 v63, v37, v2
	v_fmac_f32_e32 v61, v38, v2
	v_fmac_f32_e32 v59, v36, v2
	v_fmac_f32_e32 v57, v41, v2
	v_fmac_f32_e32 v56, v39, v2
	v_fmac_f32_e32 v54, v43, v2
	v_fmac_f32_e32 v52, v42, v2
	v_fmac_f32_e32 v71, v6, v3
	v_fmac_f32_e32 v72, v8, v3
	v_fmac_f32_e32 v81, v10, v3
	v_fmac_f32_e32 v85, v9, v3
	v_fmac_f32_e32 v90, v15, v3
	v_fmac_f32_e32 v95, v12, v3
	v_fmac_f32_e32 v99, v13, v3
	v_fmac_f32_e32 v104, v11, v3
	v_fmac_f32_e32 v107, v16, v3
	v_fmac_f32_e32 v112, v14, v3
	v_fmac_f32_e32 v117, v23, v3
	v_fmac_f32_e32 v113, v17, v3
	v_fmac_f32_e32 v108, v32, v3
	v_fmac_f32_e32 v102, v25, v3
	v_fmac_f32_e32 v98, v26, v3
	v_fmac_f32_e32 v93, v24, v3
	v_fmac_f32_e32 v88, v33, v3
	v_fmac_f32_e32 v83, v27, v3
	v_fmac_f32_e32 v79, v35, v3
	v_fmac_f32_e32 v73, v34, v3
	v_fmac_f32_e32 v68, v40, v3
	v_fmac_f32_e32 v65, v37, v3
	v_fmac_f32_e32 v63, v38, v3
	v_fmac_f32_e32 v61, v36, v3
	v_fmac_f32_e32 v59, v41, v3
	v_fmac_f32_e32 v57, v39, v3
	v_fmac_f32_e32 v56, v43, v3
	v_fmac_f32_e32 v54, v42, v3
	v_fmac_f32_e32 v52, v44, v3
	v_lshlrev_b32_e32 v3, 16, v49
	v_cndmask_b32_e64 v3, v3, 0, s[16:17]
	v_mul_f32_e32 v3, v50, v3
	v_fma_f32 v49, v7, v3, 0
	v_fmac_f32_e32 v49, v5, v51
	v_fmac_f32_e32 v49, v8, v53
	v_fmac_f32_e32 v49, v6, v55
	v_fmac_f32_e32 v49, v10, v58
	v_fmac_f32_e32 v49, v9, v60
	v_fmac_f32_e32 v49, v15, v62
	v_fmac_f32_e32 v49, v12, v64
	v_fmac_f32_e32 v49, v13, v66
	v_fmac_f32_e32 v49, v11, v69
	v_fmac_f32_e32 v49, v16, v74
	v_fmac_f32_e32 v49, v14, v80
	v_fmac_f32_e32 v49, v23, v84
	v_fmac_f32_e32 v49, v17, v89
	v_fmac_f32_e32 v49, v32, v94
	v_fmac_f32_e32 v49, v25, v100
	v_fmac_f32_e32 v49, v26, v105
	v_fmac_f32_e32 v49, v24, v110
	v_fmac_f32_e32 v49, v33, v114
	v_fmac_f32_e32 v49, v27, v118
	v_fmac_f32_e32 v49, v35, v119
	v_fmac_f32_e32 v49, v34, v116
	v_fmac_f32_e32 v49, v40, v111
	v_fmac_f32_e32 v49, v37, v106
	v_lshlrev_b32_e32 v48, 16, v48
	v_fmac_f32_e32 v49, v38, v101
	v_cndmask_b32_e64 v48, v48, 0, s[16:17]
	v_fmac_f32_e32 v49, v36, v96
	v_mul_f32_e32 v48, 0xbfb8aa3b, v48
	v_fmac_f32_e32 v49, v41, v91
	v_exp_f32_e32 v48, v48
	v_fmac_f32_e32 v49, v39, v86
	v_fmac_f32_e32 v49, v43, v77
	v_lshlrev_b32_e32 v47, 16, v47
	v_fmac_f32_e32 v49, v42, v78
	v_cndmask_b32_e64 v47, v47, 0, s[16:17]
	v_fmac_f32_e32 v49, v44, v2
	v_add_f32_e32 v2, 1.0, v48
	v_mul_f32_e32 v47, 0xbfb8aa3b, v47
	v_rcp_f32_e32 v2, v2
	v_exp_f32_e32 v47, v47
	v_lshlrev_b32_e32 v45, 16, v45
	v_cndmask_b32_e64 v45, v45, 0, s[16:17]
	v_mul_f32_e32 v2, v2, v45
	v_add_f32_e32 v45, 1.0, v47
	v_rcp_f32_e32 v45, v45
	v_fma_f32 v47, v7, v2, 0
	v_lshlrev_b32_e32 v2, 16, v46
	v_cndmask_b32_e64 v2, v2, 0, s[16:17]
	v_mul_f32_e32 v2, v45, v2
	v_fma_f32 v7, v7, v2, 0
	v_fmac_f32_e32 v47, v5, v2
	v_fmac_f32_e32 v7, v5, v3
	v_fmac_f32_e32 v47, v8, v3
	v_fmac_f32_e32 v7, v8, v51
	v_fmac_f32_e32 v72, v6, v67
	v_fmac_f32_e32 v47, v6, v51
	v_fmac_f32_e32 v7, v6, v53
	v_fmac_f32_e32 v71, v10, v67
	v_fmac_f32_e32 v72, v10, v70
	v_fmac_f32_e32 v47, v10, v53
	v_fmac_f32_e32 v7, v10, v55
	v_fmac_f32_e32 v71, v9, v70
	v_fmac_f32_e32 v72, v9, v75
	v_fmac_f32_e32 v81, v9, v67
	v_fmac_f32_e32 v47, v9, v55
	v_fmac_f32_e32 v7, v9, v58
	v_fmac_f32_e32 v71, v15, v75
	v_fmac_f32_e32 v72, v15, v82
	v_fmac_f32_e32 v81, v15, v70
	v_fmac_f32_e32 v85, v15, v67
	v_fmac_f32_e32 v47, v15, v58
	v_fmac_f32_e32 v7, v15, v60
	v_fmac_f32_e32 v71, v12, v82
	v_fmac_f32_e32 v72, v12, v87
	v_fmac_f32_e32 v81, v12, v75
	v_fmac_f32_e32 v85, v12, v70
	v_fmac_f32_e32 v90, v12, v67
	v_fmac_f32_e32 v47, v12, v60
	v_fmac_f32_e32 v7, v12, v62
	v_fmac_f32_e32 v71, v13, v87
	v_fmac_f32_e32 v72, v13, v92
	v_fmac_f32_e32 v81, v13, v82
	v_fmac_f32_e32 v85, v13, v75
	v_fmac_f32_e32 v90, v13, v70
	v_fmac_f32_e32 v95, v13, v67
	v_fmac_f32_e32 v47, v13, v62
	v_fmac_f32_e32 v7, v13, v64
	v_fmac_f32_e32 v71, v11, v92
	v_fmac_f32_e32 v72, v11, v97
	v_fmac_f32_e32 v81, v11, v87
	v_fmac_f32_e32 v85, v11, v82
	v_fmac_f32_e32 v90, v11, v75
	v_fmac_f32_e32 v95, v11, v70
	v_fmac_f32_e32 v99, v11, v67
	v_fmac_f32_e32 v47, v11, v64
	v_fmac_f32_e32 v7, v11, v66
	v_fmac_f32_e32 v71, v16, v97
	v_fmac_f32_e32 v72, v16, v103
	v_fmac_f32_e32 v81, v16, v92
	v_fmac_f32_e32 v85, v16, v87
	v_fmac_f32_e32 v90, v16, v82
	v_fmac_f32_e32 v95, v16, v75
	v_fmac_f32_e32 v99, v16, v70
	v_fmac_f32_e32 v104, v16, v67
	v_fmac_f32_e32 v47, v16, v66
	v_fmac_f32_e32 v7, v16, v69
	v_fmac_f32_e32 v71, v14, v103
	v_fmac_f32_e32 v72, v14, v109
	v_fmac_f32_e32 v81, v14, v97
	v_fmac_f32_e32 v85, v14, v92
	v_fmac_f32_e32 v90, v14, v87
	v_fmac_f32_e32 v95, v14, v82
	v_fmac_f32_e32 v99, v14, v75
	v_fmac_f32_e32 v104, v14, v70
	v_fmac_f32_e32 v107, v14, v67
	v_fmac_f32_e32 v47, v14, v69
	v_fmac_f32_e32 v7, v14, v74
	v_fmac_f32_e32 v71, v23, v109
	v_fmac_f32_e32 v72, v23, v115
	v_fmac_f32_e32 v81, v23, v103
	v_fmac_f32_e32 v85, v23, v97
	v_fmac_f32_e32 v90, v23, v92
	v_fmac_f32_e32 v95, v23, v87
	v_fmac_f32_e32 v99, v23, v82
	v_fmac_f32_e32 v104, v23, v75
	v_fmac_f32_e32 v107, v23, v70
	v_fmac_f32_e32 v112, v23, v67
	v_fmac_f32_e32 v47, v23, v74
	v_fmac_f32_e32 v7, v23, v80
	v_fmac_f32_e32 v71, v17, v115
	v_fmac_f32_e32 v72, v17, v120
	v_fmac_f32_e32 v81, v17, v109
	v_fmac_f32_e32 v85, v17, v103
	v_fmac_f32_e32 v90, v17, v97
	v_fmac_f32_e32 v95, v17, v92
	v_fmac_f32_e32 v99, v17, v87
	v_fmac_f32_e32 v104, v17, v82
	v_fmac_f32_e32 v107, v17, v75
	v_fmac_f32_e32 v112, v17, v70
	v_fmac_f32_e32 v117, v17, v67
	v_fmac_f32_e32 v47, v17, v80
	v_fmac_f32_e32 v7, v17, v84
	v_fmac_f32_e32 v71, v32, v120
	v_fmac_f32_e32 v72, v32, v121
	v_fmac_f32_e32 v81, v32, v115
	v_fmac_f32_e32 v85, v32, v109
	v_fmac_f32_e32 v90, v32, v103
	v_fmac_f32_e32 v95, v32, v97
	v_fmac_f32_e32 v99, v32, v92
	v_fmac_f32_e32 v104, v32, v87
	v_fmac_f32_e32 v107, v32, v82
	v_fmac_f32_e32 v112, v32, v75
	v_fmac_f32_e32 v117, v32, v70
	v_fmac_f32_e32 v113, v32, v67
	v_fmac_f32_e32 v47, v32, v84
	v_fmac_f32_e32 v7, v32, v89
	v_fmac_f32_e32 v71, v25, v121
	v_fmac_f32_e32 v72, v25, v122
	v_fmac_f32_e32 v81, v25, v120
	v_fmac_f32_e32 v85, v25, v115
	v_fmac_f32_e32 v90, v25, v109
	v_fmac_f32_e32 v95, v25, v103
	v_fmac_f32_e32 v99, v25, v97
	v_fmac_f32_e32 v104, v25, v92
	v_fmac_f32_e32 v107, v25, v87
	v_fmac_f32_e32 v112, v25, v82
	v_fmac_f32_e32 v117, v25, v75
	v_fmac_f32_e32 v113, v25, v70
	v_fmac_f32_e32 v108, v25, v67
	v_fmac_f32_e32 v47, v25, v89
	v_fmac_f32_e32 v7, v25, v94
	v_fmac_f32_e32 v71, v26, v122
	v_fmac_f32_e32 v72, v26, v123
	v_fmac_f32_e32 v81, v26, v121
	v_fmac_f32_e32 v85, v26, v120
	v_fmac_f32_e32 v90, v26, v115
	v_fmac_f32_e32 v95, v26, v109
	v_fmac_f32_e32 v99, v26, v103
	v_fmac_f32_e32 v104, v26, v97
	v_fmac_f32_e32 v107, v26, v92
	v_fmac_f32_e32 v112, v26, v87
	v_fmac_f32_e32 v117, v26, v82
	v_fmac_f32_e32 v113, v26, v75
	v_fmac_f32_e32 v108, v26, v70
	v_fmac_f32_e32 v102, v26, v67
	v_fmac_f32_e32 v47, v26, v94
	v_fmac_f32_e32 v7, v26, v100
	v_fmac_f32_e32 v71, v24, v123
	v_fmac_f32_e32 v72, v24, v124
	v_fmac_f32_e32 v81, v24, v122
	v_fmac_f32_e32 v85, v24, v121
	v_fmac_f32_e32 v90, v24, v120
	v_fmac_f32_e32 v95, v24, v115
	v_fmac_f32_e32 v99, v24, v109
	v_fmac_f32_e32 v104, v24, v103
	v_fmac_f32_e32 v107, v24, v97
	v_fmac_f32_e32 v112, v24, v92
	v_fmac_f32_e32 v117, v24, v87
	v_fmac_f32_e32 v113, v24, v82
	v_fmac_f32_e32 v108, v24, v75
	v_fmac_f32_e32 v102, v24, v70
	v_fmac_f32_e32 v98, v24, v67
	v_fmac_f32_e32 v47, v24, v100
	v_fmac_f32_e32 v7, v24, v105
	v_fmac_f32_e32 v71, v33, v124
	v_fmac_f32_e32 v72, v33, v125
	v_fmac_f32_e32 v81, v33, v123
	v_fmac_f32_e32 v85, v33, v122
	v_fmac_f32_e32 v90, v33, v121
	v_fmac_f32_e32 v95, v33, v120
	v_fmac_f32_e32 v99, v33, v115
	v_fmac_f32_e32 v104, v33, v109
	v_fmac_f32_e32 v107, v33, v103
	v_fmac_f32_e32 v112, v33, v97
	v_fmac_f32_e32 v117, v33, v92
	v_fmac_f32_e32 v113, v33, v87
	v_fmac_f32_e32 v108, v33, v82
	v_fmac_f32_e32 v102, v33, v75
	v_fmac_f32_e32 v98, v33, v70
	v_fmac_f32_e32 v93, v33, v67
	v_fmac_f32_e32 v47, v33, v105
	v_fmac_f32_e32 v7, v33, v110
	v_fmac_f32_e32 v71, v27, v125
	v_fmac_f32_e32 v72, v27, v126
	v_fmac_f32_e32 v81, v27, v124
	v_fmac_f32_e32 v85, v27, v123
	v_fmac_f32_e32 v90, v27, v122
	v_fmac_f32_e32 v95, v27, v121
	v_fmac_f32_e32 v99, v27, v120
	v_fmac_f32_e32 v104, v27, v115
	v_fmac_f32_e32 v107, v27, v109
	v_fmac_f32_e32 v112, v27, v103
	v_fmac_f32_e32 v117, v27, v97
	v_fmac_f32_e32 v113, v27, v92
	v_fmac_f32_e32 v108, v27, v87
	v_fmac_f32_e32 v102, v27, v82
	v_fmac_f32_e32 v98, v27, v75
	v_fmac_f32_e32 v93, v27, v70
	v_fmac_f32_e32 v88, v27, v67
	v_fmac_f32_e32 v47, v27, v110
	v_fmac_f32_e32 v7, v27, v114
	v_fmac_f32_e32 v71, v35, v126
	v_fmac_f32_e32 v72, v35, v127
	v_fmac_f32_e32 v81, v35, v125
	v_fmac_f32_e32 v85, v35, v124
	v_fmac_f32_e32 v90, v35, v123
	v_fmac_f32_e32 v95, v35, v122
	v_fmac_f32_e32 v99, v35, v121
	v_fmac_f32_e32 v104, v35, v120
	v_fmac_f32_e32 v107, v35, v115
	v_fmac_f32_e32 v112, v35, v109
	v_fmac_f32_e32 v117, v35, v103
	v_fmac_f32_e32 v113, v35, v97
	v_fmac_f32_e32 v108, v35, v92
	v_fmac_f32_e32 v102, v35, v87
	v_fmac_f32_e32 v98, v35, v82
	v_fmac_f32_e32 v93, v35, v75
	v_fmac_f32_e32 v88, v35, v70
	v_fmac_f32_e32 v83, v35, v67
	v_fmac_f32_e32 v47, v35, v114
	v_fmac_f32_e32 v7, v35, v118
	v_fmac_f32_e32 v71, v34, v127
	v_fmac_f32_e32 v72, v34, v128
	v_fmac_f32_e32 v81, v34, v126
	v_fmac_f32_e32 v85, v34, v125
	v_fmac_f32_e32 v90, v34, v124
	v_fmac_f32_e32 v95, v34, v123
	v_fmac_f32_e32 v99, v34, v122
	v_fmac_f32_e32 v104, v34, v121
	v_fmac_f32_e32 v107, v34, v120
	v_fmac_f32_e32 v112, v34, v115
	v_fmac_f32_e32 v117, v34, v109
	v_fmac_f32_e32 v113, v34, v103
	v_fmac_f32_e32 v108, v34, v97
	v_fmac_f32_e32 v102, v34, v92
	v_fmac_f32_e32 v98, v34, v87
	v_fmac_f32_e32 v93, v34, v82
	v_fmac_f32_e32 v88, v34, v75
	v_fmac_f32_e32 v83, v34, v70
	v_fmac_f32_e32 v79, v34, v67
	v_fmac_f32_e32 v47, v34, v118
	v_fmac_f32_e32 v7, v34, v119
	v_fmac_f32_e32 v71, v40, v128
	v_fmac_f32_e32 v72, v40, v129
	v_fmac_f32_e32 v81, v40, v127
	v_fmac_f32_e32 v85, v40, v126
	v_fmac_f32_e32 v90, v40, v125
	v_fmac_f32_e32 v95, v40, v124
	v_fmac_f32_e32 v99, v40, v123
	v_fmac_f32_e32 v104, v40, v122
	v_fmac_f32_e32 v107, v40, v121
	v_fmac_f32_e32 v112, v40, v120
	v_fmac_f32_e32 v117, v40, v115
	v_fmac_f32_e32 v113, v40, v109
	v_fmac_f32_e32 v108, v40, v103
	v_fmac_f32_e32 v102, v40, v97
	v_fmac_f32_e32 v98, v40, v92
	v_fmac_f32_e32 v93, v40, v87
	v_fmac_f32_e32 v88, v40, v82
	v_fmac_f32_e32 v83, v40, v75
	v_fmac_f32_e32 v79, v40, v70
	v_fmac_f32_e32 v73, v40, v67
	v_fmac_f32_e32 v47, v40, v119
	v_fmac_f32_e32 v7, v40, v116
	v_fmac_f32_e32 v71, v37, v129
	v_fmac_f32_e32 v72, v37, v130
	v_fmac_f32_e32 v81, v37, v128
	v_fmac_f32_e32 v85, v37, v127
	v_fmac_f32_e32 v90, v37, v126
	v_fmac_f32_e32 v95, v37, v125
	v_fmac_f32_e32 v99, v37, v124
	v_fmac_f32_e32 v104, v37, v123
	v_fmac_f32_e32 v107, v37, v122
	v_fmac_f32_e32 v112, v37, v121
	v_fmac_f32_e32 v117, v37, v120
	v_fmac_f32_e32 v113, v37, v115
	v_fmac_f32_e32 v108, v37, v109
	v_fmac_f32_e32 v102, v37, v103
	v_fmac_f32_e32 v98, v37, v97
	v_fmac_f32_e32 v93, v37, v92
	v_fmac_f32_e32 v88, v37, v87
	v_fmac_f32_e32 v83, v37, v82
	v_fmac_f32_e32 v79, v37, v75
	v_fmac_f32_e32 v73, v37, v70
	v_fmac_f32_e32 v68, v37, v67
	v_fmac_f32_e32 v47, v37, v116
	v_fmac_f32_e32 v7, v37, v111
	v_fmac_f32_e32 v71, v38, v130
	v_fmac_f32_e32 v72, v38, v131
	v_fmac_f32_e32 v81, v38, v129
	v_fmac_f32_e32 v85, v38, v128
	v_fmac_f32_e32 v90, v38, v127
	v_fmac_f32_e32 v95, v38, v126
	v_fmac_f32_e32 v99, v38, v125
	v_fmac_f32_e32 v104, v38, v124
	v_fmac_f32_e32 v107, v38, v123
	v_fmac_f32_e32 v112, v38, v122
	v_fmac_f32_e32 v117, v38, v121
	v_fmac_f32_e32 v113, v38, v120
	v_fmac_f32_e32 v108, v38, v115
	v_fmac_f32_e32 v102, v38, v109
	v_fmac_f32_e32 v98, v38, v103
	v_fmac_f32_e32 v93, v38, v97
	v_fmac_f32_e32 v88, v38, v92
	v_fmac_f32_e32 v83, v38, v87
	v_fmac_f32_e32 v79, v38, v82
	v_fmac_f32_e32 v73, v38, v75
	v_fmac_f32_e32 v68, v38, v70
	v_fmac_f32_e32 v65, v38, v67
	v_fmac_f32_e32 v47, v38, v111
	v_fmac_f32_e32 v7, v38, v106
	v_fmac_f32_e32 v71, v36, v131
	v_fmac_f32_e32 v72, v36, v132
	v_fmac_f32_e32 v81, v36, v130
	v_fmac_f32_e32 v85, v36, v129
	v_fmac_f32_e32 v90, v36, v128
	v_fmac_f32_e32 v95, v36, v127
	v_fmac_f32_e32 v99, v36, v126
	v_fmac_f32_e32 v104, v36, v125
	v_fmac_f32_e32 v107, v36, v124
	v_fmac_f32_e32 v112, v36, v123
	v_fmac_f32_e32 v117, v36, v122
	v_fmac_f32_e32 v113, v36, v121
	v_fmac_f32_e32 v108, v36, v120
	v_fmac_f32_e32 v102, v36, v115
	v_fmac_f32_e32 v98, v36, v109
	v_fmac_f32_e32 v93, v36, v103
	v_fmac_f32_e32 v88, v36, v97
	v_fmac_f32_e32 v83, v36, v92
	v_fmac_f32_e32 v79, v36, v87
	v_fmac_f32_e32 v73, v36, v82
	v_fmac_f32_e32 v68, v36, v75
	v_fmac_f32_e32 v65, v36, v70
	v_fmac_f32_e32 v63, v36, v67
	v_fmac_f32_e32 v47, v36, v106
	v_fmac_f32_e32 v7, v36, v101
	v_fmac_f32_e32 v71, v41, v132
	v_fmac_f32_e32 v72, v41, v140
	v_fmac_f32_e32 v81, v41, v131
	v_fmac_f32_e32 v85, v41, v130
	v_fmac_f32_e32 v90, v41, v129
	v_fmac_f32_e32 v95, v41, v128
	v_fmac_f32_e32 v99, v41, v127
	v_fmac_f32_e32 v104, v41, v126
	v_fmac_f32_e32 v107, v41, v125
	v_fmac_f32_e32 v112, v41, v124
	v_fmac_f32_e32 v117, v41, v123
	v_fmac_f32_e32 v113, v41, v122
	v_fmac_f32_e32 v108, v41, v121
	v_fmac_f32_e32 v102, v41, v120
	v_fmac_f32_e32 v98, v41, v115
	v_fmac_f32_e32 v93, v41, v109
	v_fmac_f32_e32 v88, v41, v103
	v_fmac_f32_e32 v83, v41, v97
	v_fmac_f32_e32 v79, v41, v92
	v_fmac_f32_e32 v73, v41, v87
	v_fmac_f32_e32 v68, v41, v82
	v_fmac_f32_e32 v65, v41, v75
	v_fmac_f32_e32 v63, v41, v70
	v_fmac_f32_e32 v61, v41, v67
	v_fmac_f32_e32 v47, v41, v101
	v_fmac_f32_e32 v7, v41, v96
	v_fmac_f32_e32 v71, v39, v140
	v_fmac_f32_e32 v72, v39, v136
	v_fmac_f32_e32 v81, v39, v132
	v_fmac_f32_e32 v85, v39, v131
	v_fmac_f32_e32 v90, v39, v130
	v_fmac_f32_e32 v95, v39, v129
	v_fmac_f32_e32 v99, v39, v128
	v_fmac_f32_e32 v104, v39, v127
	v_fmac_f32_e32 v107, v39, v126
	v_fmac_f32_e32 v112, v39, v125
	v_fmac_f32_e32 v117, v39, v124
	v_fmac_f32_e32 v113, v39, v123
	v_fmac_f32_e32 v108, v39, v122
	v_fmac_f32_e32 v102, v39, v121
	v_fmac_f32_e32 v98, v39, v120
	v_fmac_f32_e32 v93, v39, v115
	v_fmac_f32_e32 v88, v39, v109
	v_fmac_f32_e32 v83, v39, v103
	v_fmac_f32_e32 v79, v39, v97
	v_fmac_f32_e32 v73, v39, v92
	v_fmac_f32_e32 v68, v39, v87
	v_fmac_f32_e32 v65, v39, v82
	v_fmac_f32_e32 v63, v39, v75
	v_fmac_f32_e32 v61, v39, v70
	v_fmac_f32_e32 v59, v39, v67
	v_fmac_f32_e32 v47, v39, v96
	v_fmac_f32_e32 v7, v39, v91
	v_fmac_f32_e32 v71, v43, v136
	v_fmac_f32_e32 v72, v43, v137
	v_fmac_f32_e32 v81, v43, v140
	v_fmac_f32_e32 v85, v43, v132
	v_fmac_f32_e32 v90, v43, v131
	v_fmac_f32_e32 v95, v43, v130
	v_fmac_f32_e32 v99, v43, v129
	v_fmac_f32_e32 v104, v43, v128
	v_fmac_f32_e32 v107, v43, v127
	v_fmac_f32_e32 v112, v43, v126
	v_fmac_f32_e32 v117, v43, v125
	v_fmac_f32_e32 v113, v43, v124
	v_fmac_f32_e32 v108, v43, v123
	v_fmac_f32_e32 v102, v43, v122
	v_fmac_f32_e32 v98, v43, v121
	v_fmac_f32_e32 v93, v43, v120
	v_fmac_f32_e32 v88, v43, v115
	v_fmac_f32_e32 v83, v43, v109
	v_fmac_f32_e32 v79, v43, v103
	v_fmac_f32_e32 v73, v43, v97
	v_fmac_f32_e32 v68, v43, v92
	v_fmac_f32_e32 v65, v43, v87
	v_fmac_f32_e32 v63, v43, v82
	v_fmac_f32_e32 v61, v43, v75
	v_fmac_f32_e32 v59, v43, v70
	v_fmac_f32_e32 v57, v43, v67
	v_fmac_f32_e32 v47, v43, v91
	v_fmac_f32_e32 v7, v43, v86
	v_fmac_f32_e32 v71, v42, v137
	v_fmac_f32_e32 v72, v42, v134
	v_fmac_f32_e32 v81, v42, v136
	v_fmac_f32_e32 v85, v42, v140
	v_fmac_f32_e32 v90, v42, v132
	v_fmac_f32_e32 v95, v42, v131
	v_fmac_f32_e32 v99, v42, v130
	v_fmac_f32_e32 v104, v42, v129
	v_fmac_f32_e32 v107, v42, v128
	v_fmac_f32_e32 v112, v42, v127
	v_fmac_f32_e32 v117, v42, v126
	v_fmac_f32_e32 v113, v42, v125
	v_fmac_f32_e32 v108, v42, v124
	v_fmac_f32_e32 v102, v42, v123
	v_fmac_f32_e32 v98, v42, v122
	v_fmac_f32_e32 v93, v42, v121
	v_fmac_f32_e32 v88, v42, v120
	v_fmac_f32_e32 v83, v42, v115
	v_fmac_f32_e32 v79, v42, v109
	v_fmac_f32_e32 v73, v42, v103
	v_fmac_f32_e32 v68, v42, v97
	v_fmac_f32_e32 v65, v42, v92
	v_fmac_f32_e32 v63, v42, v87
	v_fmac_f32_e32 v61, v42, v82
	v_fmac_f32_e32 v59, v42, v75
	v_fmac_f32_e32 v57, v42, v70
	v_fmac_f32_e32 v56, v42, v67
	v_fmac_f32_e32 v47, v42, v86
	v_fmac_f32_e32 v7, v42, v77
	s_xor_b64 s[4:5], s[52:53], -1
	v_fmac_f32_e32 v71, v44, v134
	v_fmac_f32_e32 v81, v44, v137
	v_fmac_f32_e32 v85, v44, v136
	v_fmac_f32_e32 v90, v44, v140
	v_fmac_f32_e32 v95, v44, v132
	v_fmac_f32_e32 v99, v44, v131
	v_fmac_f32_e32 v104, v44, v130
	v_fmac_f32_e32 v107, v44, v129
	v_fmac_f32_e32 v112, v44, v128
	v_fmac_f32_e32 v117, v44, v127
	v_fmac_f32_e32 v113, v44, v126
	v_fmac_f32_e32 v108, v44, v125
	v_fmac_f32_e32 v102, v44, v124
	v_fmac_f32_e32 v98, v44, v123
	v_fmac_f32_e32 v93, v44, v122
	v_fmac_f32_e32 v88, v44, v121
	v_fmac_f32_e32 v83, v44, v120
	v_fmac_f32_e32 v79, v44, v115
	v_fmac_f32_e32 v73, v44, v109
	v_fmac_f32_e32 v68, v44, v103
	v_fmac_f32_e32 v65, v44, v97
	v_fmac_f32_e32 v63, v44, v92
	v_fmac_f32_e32 v61, v44, v87
	v_fmac_f32_e32 v59, v44, v82
	v_fmac_f32_e32 v57, v44, v75
	v_fmac_f32_e32 v56, v44, v70
	v_fmac_f32_e32 v54, v44, v67
	v_fmac_f32_e32 v47, v44, v77
	v_fmac_f32_e32 v7, v44, v78
	v_fmac_f32_e32 v72, v44, v76
	v_readlane_b32 s52, v236, 19
	v_readlane_b32 s53, v236, 20
	s_and_b64 vcc, exec, s[4:5]
	s_nop 0
	v_lshl_add_u64 v[2:3], v[18:19], 2, s[52:53]
	global_load_dword v2, v[2:3], off
	v_lshl_add_u32 v3, s33, 2, v178
	s_movk_i32 s33, 0x100
	s_mov_b64 s[52:53], 0
	s_waitcnt vmcnt(0) lgkmcnt(0)
	v_add_f32_e32 v5, v47, v2
	v_add_f32_e32 v6, v7, v2
	v_add_f32_e32 v7, v49, v2
	v_add_f32_e32 v8, v52, v2
	v_add_f32_e32 v9, v54, v2
	v_add_f32_e32 v10, v56, v2
	v_add_f32_e32 v11, v57, v2
	v_add_f32_e32 v12, v59, v2
	v_add_f32_e32 v13, v61, v2
	v_add_f32_e32 v14, v63, v2
	v_add_f32_e32 v15, v65, v2
	v_add_f32_e32 v16, v68, v2
	v_add_f32_e32 v17, v73, v2
	v_add_f32_e32 v18, v79, v2
	v_add_f32_e32 v23, v83, v2
	v_add_f32_e32 v24, v88, v2
	v_add_f32_e32 v25, v93, v2
	v_add_f32_e32 v26, v98, v2
	v_add_f32_e32 v27, v102, v2
	v_add_f32_e32 v32, v108, v2
	v_add_f32_e32 v33, v113, v2
	v_add_f32_e32 v34, v117, v2
	v_add_f32_e32 v35, v112, v2
	v_add_f32_e32 v36, v107, v2
	v_add_f32_e32 v37, v104, v2
	v_add_f32_e32 v38, v99, v2
	v_add_f32_e32 v39, v95, v2
	v_add_f32_e32 v40, v90, v2
	v_add_f32_e32 v41, v85, v2
	v_add_f32_e32 v42, v81, v2
	v_add_f32_e32 v43, v71, v2
	v_add_f32_e32 v2, v72, v2
	ds_write2st64_b32 v3, v5, v6 offset1:8
	ds_write2st64_b32 v3, v7, v8 offset0:16 offset1:24
	ds_write2st64_b32 v3, v9, v10 offset0:32 offset1:40
	ds_write2st64_b32 v3, v11, v12 offset0:48 offset1:56
	ds_write2st64_b32 v3, v13, v14 offset0:64 offset1:72
	ds_write2st64_b32 v3, v15, v16 offset0:80 offset1:88
	ds_write2st64_b32 v3, v17, v18 offset0:96 offset1:104
	ds_write2st64_b32 v3, v23, v24 offset0:112 offset1:120
	ds_write2st64_b32 v3, v25, v26 offset0:128 offset1:136
	ds_write2st64_b32 v3, v27, v32 offset0:144 offset1:152
	ds_write2st64_b32 v3, v33, v34 offset0:160 offset1:168
	ds_write2st64_b32 v3, v35, v36 offset0:176 offset1:184
	ds_write2st64_b32 v3, v37, v38 offset0:192 offset1:200
	ds_write2st64_b32 v3, v39, v40 offset0:208 offset1:216
	ds_write2st64_b32 v3, v41, v42 offset0:224 offset1:232
	ds_write2st64_b32 v3, v43, v2 offset0:240 offset1:248
	s_cbranch_vccnz .LBB0_512
.LBB0_452:
	v_add_u32_e32 v18, s33, v0
	v_lshl_add_u64 v[2:3], v[18:19], 2, s[66:67]
	v_add_co_u32_e32 v10, vcc, 0x1000, v2
	global_load_dword v7, v[2:3], off
	global_load_dword v5, v[2:3], off offset:2048
	v_addc_co_u32_e32 v11, vcc, 0, v3, vcc
	v_add_co_u32_e32 v12, vcc, 0x2000, v2
	global_load_dword v8, v[10:11], off
	global_load_dword v6, v[10:11], off offset:2048
	v_addc_co_u32_e32 v13, vcc, 0, v3, vcc
	global_load_dword v10, v[12:13], off
	global_load_dword v9, v[12:13], off offset:2048
	v_add_co_u32_e32 v12, vcc, 0x3000, v2
	v_readlane_b32 s4, v236, 11
	s_nop 0
	v_addc_co_u32_e32 v13, vcc, 0, v3, vcc
	v_add_co_u32_e32 v16, vcc, 0x4000, v2
	global_load_dword v15, v[12:13], off
	s_nop 0
	global_load_dword v12, v[12:13], off offset:2048
	v_addc_co_u32_e32 v17, vcc, 0, v3, vcc
	v_add_co_u32_e32 v24, vcc, 0x5000, v2
	global_load_dword v13, v[16:17], off
	global_load_dword v11, v[16:17], off offset:2048
	v_addc_co_u32_e32 v25, vcc, 0, v3, vcc
	global_load_dword v16, v[24:25], off
	global_load_dword v14, v[24:25], off offset:2048
	v_add_co_u32_e32 v24, vcc, 0x6000, v2
	v_readlane_b32 s5, v236, 12
	s_nop 0
	v_addc_co_u32_e32 v25, vcc, 0, v3, vcc
	global_load_dword v23, v[24:25], off
	global_load_dword v17, v[24:25], off offset:2048
	v_add_co_u32_e32 v24, vcc, 0x7000, v2
	s_nop 1
	v_addc_co_u32_e32 v25, vcc, 0, v3, vcc
	v_add_co_u32_e32 v34, vcc, 0x8000, v2
	global_load_dword v32, v[24:25], off
	s_nop 0
	global_load_dword v25, v[24:25], off offset:2048
	v_addc_co_u32_e32 v35, vcc, 0, v3, vcc
	global_load_dword v26, v[34:35], off
	global_load_dword v24, v[34:35], off offset:2048
	v_add_co_u32_e32 v34, vcc, 0x9000, v2
	s_nop 1
	v_addc_co_u32_e32 v35, vcc, 0, v3, vcc
	v_add_co_u32_e32 v36, vcc, 0xa000, v2
	global_load_dword v33, v[34:35], off
	global_load_dword v27, v[34:35], off offset:2048
	v_addc_co_u32_e32 v37, vcc, 0, v3, vcc
	global_load_dword v35, v[36:37], off
	global_load_dword v34, v[36:37], off offset:2048
	v_add_co_u32_e32 v36, vcc, 0xb000, v2
	s_nop 1
	v_addc_co_u32_e32 v37, vcc, 0, v3, vcc
	v_add_co_u32_e32 v42, vcc, 0xc000, v2
	global_load_dword v40, v[36:37], off
	s_nop 0
	global_load_dword v37, v[36:37], off offset:2048
	v_addc_co_u32_e32 v43, vcc, 0, v3, vcc
	global_load_dword v38, v[42:43], off
	global_load_dword v36, v[42:43], off offset:2048
	v_add_co_u32_e32 v42, vcc, 0xd000, v2
	s_nop 1
	v_addc_co_u32_e32 v43, vcc, 0, v3, vcc
	v_add_co_u32_e32 v44, vcc, 0xe000, v2
	global_load_dword v41, v[42:43], off
	global_load_dword v39, v[42:43], off offset:2048
	v_addc_co_u32_e32 v45, vcc, 0, v3, vcc
	v_add_co_u32_e32 v2, vcc, 0xf000, v2
	global_load_dword v43, v[44:45], off
	global_load_dword v42, v[44:45], off offset:2048
	v_addc_co_u32_e32 v3, vcc, 0, v3, vcc
	global_load_dword v44, v[2:3], off
	v_lshlrev_b64 v[2:3], 1, v[18:19]
	v_lshl_add_u64 v[46:47], s[4:5], 0, v[2:3]
	v_readlane_b32 s4, v236, 15
	v_readlane_b32 s5, v236, 16
	v_lshl_add_u64 v[50:51], s[70:71], 0, v[2:3]
	global_load_ushort v45, v[46:47], off
	global_load_ushort v48, v[46:47], off offset:1024
	v_lshl_add_u64 v[54:55], s[4:5], 0, v[2:3]
	v_readlane_b32 s4, v236, 17
	v_readlane_b32 s5, v236, 18
	global_load_ushort v46, v[50:51], off
	global_load_ushort v47, v[50:51], off offset:1024
	v_lshl_add_u64 v[56:57], s[4:5], 0, v[2:3]
	v_readlane_b32 s4, v236, 13
	v_readlane_b32 s5, v236, 14
	v_lshl_add_u64 v[50:51], s[74:75], 0, v[2:3]
	v_lshl_add_u64 v[52:53], s[72:73], 0, v[2:3]
	v_lshl_add_u64 v[58:59], s[4:5], 0, v[2:3]
	v_lshl_add_u64 v[60:61], s[76:77], 0, v[2:3]
	v_lshl_add_u64 v[62:63], s[78:79], 0, v[2:3]
	v_lshl_add_u64 v[64:65], s[80:81], 0, v[2:3]
	v_lshl_add_u64 v[66:67], s[84:85], 0, v[2:3]
	v_lshl_add_u64 v[70:71], s[82:83], 0, v[2:3]
	global_load_ushort v49, v[50:51], off
	s_nop 0
	global_load_ushort v50, v[50:51], off offset:1024
	s_nop 0
	global_load_ushort v51, v[52:53], off
	s_nop 0
	global_load_ushort v52, v[52:53], off offset:1024
	s_nop 0
	global_load_ushort v53, v[54:55], off
	s_nop 0
	global_load_ushort v54, v[54:55], off offset:1024
	s_nop 0
	global_load_ushort v55, v[56:57], off
	s_nop 0
	global_load_ushort v56, v[56:57], off offset:1024
	s_nop 0
	global_load_ushort v57, v[58:59], off
	s_nop 0
	global_load_ushort v58, v[58:59], off offset:1024
	s_nop 0
	global_load_ushort v59, v[60:61], off
	s_nop 0
	global_load_ushort v60, v[60:61], off offset:1024
	s_nop 0
	global_load_ushort v61, v[62:63], off
	s_nop 0
	global_load_ushort v62, v[62:63], off offset:1024
	s_nop 0
	global_load_ushort v63, v[64:65], off
	s_nop 0
	global_load_ushort v64, v[64:65], off offset:1024
	s_nop 0
	global_load_ushort v65, v[66:67], off
	s_nop 0
	global_load_ushort v66, v[66:67], off offset:1024
	s_nop 0
	global_load_ushort v68, v[70:71], off
	global_load_ushort v69, v[70:71], off offset:1024
	v_lshl_add_u64 v[70:71], s[62:63], 0, v[2:3]
	global_load_ushort v73, v[70:71], off
	global_load_ushort v74, v[70:71], off offset:1024
	v_lshl_add_u64 v[70:71], s[14:15], 0, v[2:3]
	global_load_ushort v79, v[70:71], off
	global_load_ushort v80, v[70:71], off offset:1024
	v_lshl_add_u64 v[70:71], s[54:55], 0, v[2:3]
	global_load_ushort v83, v[70:71], off
	global_load_ushort v84, v[70:71], off offset:1024
	v_lshl_add_u64 v[70:71], s[56:57], 0, v[2:3]
	global_load_ushort v88, v[70:71], off
	global_load_ushort v89, v[70:71], off offset:1024
	v_lshl_add_u64 v[70:71], s[58:59], 0, v[2:3]
	global_load_ushort v93, v[70:71], off
	global_load_ushort v94, v[70:71], off offset:1024
	v_lshl_add_u64 v[70:71], s[60:61], 0, v[2:3]
	global_load_ushort v98, v[70:71], off
	global_load_ushort v100, v[70:71], off offset:1024
	v_lshl_add_u64 v[70:71], s[86:87], 0, v[2:3]
	global_load_ushort v102, v[70:71], off
	global_load_ushort v105, v[70:71], off offset:1024
	v_lshl_add_u64 v[70:71], s[88:89], 0, v[2:3]
	global_load_ushort v108, v[70:71], off
	global_load_ushort v110, v[70:71], off offset:1024
	v_lshl_add_u64 v[70:71], s[90:91], 0, v[2:3]
	global_load_ushort v113, v[70:71], off
	global_load_ushort v114, v[70:71], off offset:1024
	v_lshl_add_u64 v[70:71], s[64:65], 0, v[2:3]
	global_load_ushort v117, v[70:71], off
	global_load_ushort v118, v[70:71], off offset:1024
	v_lshl_add_u64 v[70:71], s[94:95], 0, v[2:3]
	global_load_ushort v112, v[70:71], off
	global_load_ushort v119, v[70:71], off offset:1024
	v_lshl_add_u64 v[70:71], s[92:93], 0, v[2:3]
	v_readlane_b32 s4, v236, 21
	global_load_ushort v107, v[70:71], off
	global_load_ushort v116, v[70:71], off offset:1024
	v_lshl_add_u64 v[70:71], s[96:97], 0, v[2:3]
	v_readlane_b32 s5, v236, 22
	global_load_ushort v104, v[70:71], off
	global_load_ushort v111, v[70:71], off offset:1024
	v_lshl_add_u64 v[70:71], s[4:5], 0, v[2:3]
	v_readlane_b32 s4, v236, 23
	v_readlane_b32 s5, v236, 24
	global_load_ushort v99, v[70:71], off
	global_load_ushort v106, v[70:71], off offset:1024
	v_lshl_add_u64 v[70:71], s[4:5], 0, v[2:3]
	v_readlane_b32 s4, v236, 25
	v_readlane_b32 s5, v236, 26
	global_load_ushort v95, v[70:71], off
	global_load_ushort v101, v[70:71], off offset:1024
	v_lshl_add_u64 v[70:71], s[4:5], 0, v[2:3]
	v_readlane_b32 s4, v236, 27
	v_readlane_b32 s5, v236, 28
	global_load_ushort v90, v[70:71], off
	global_load_ushort v96, v[70:71], off offset:1024
	v_lshl_add_u64 v[70:71], s[4:5], 0, v[2:3]
	v_readlane_b32 s4, v236, 29
	v_readlane_b32 s5, v236, 30
	global_load_ushort v85, v[70:71], off
	global_load_ushort v91, v[70:71], off offset:1024
	v_lshl_add_u64 v[70:71], s[4:5], 0, v[2:3]
	v_readlane_b32 s4, v236, 31
	v_readlane_b32 s5, v236, 32
	global_load_ushort v81, v[70:71], off
	global_load_ushort v86, v[70:71], off offset:1024
	v_lshl_add_u64 v[76:77], s[4:5], 0, v[2:3]
	v_readlane_b32 s4, v236, 33
	v_readlane_b32 s5, v236, 34
	global_load_ushort v71, v[76:77], off
	global_load_ushort v72, v[76:77], off offset:1024
	v_lshl_add_u64 v[76:77], s[4:5], 0, v[2:3]
	global_load_ushort v78, v[76:77], off
	s_nop 0
	global_load_ushort v77, v[76:77], off offset:1024
	v_readlane_b32 s4, v236, 35
	v_readlane_b32 s5, v236, 36
	v_lshl_add_u64 v[122:123], s[10:11], 0, v[2:3]
	v_lshl_add_u64 v[124:125], s[18:19], 0, v[2:3]
	v_lshl_add_u64 v[120:121], s[4:5], 0, v[2:3]
	v_readlane_b32 s4, v236, 37
	v_readlane_b32 s5, v236, 38
	global_load_ushort v167, v[120:121], off
	global_load_ushort v173, v[120:121], off offset:1024
	v_lshl_add_u64 v[120:121], s[4:5], 0, v[2:3]
	v_readlane_b32 s4, v236, 39
	v_readlane_b32 s5, v236, 40
	global_load_ushort v164, v[120:121], off
	global_load_ushort v166, v[120:121], off offset:1024
	v_lshl_add_u64 v[120:121], s[4:5], 0, v[2:3]
	v_readlane_b32 s4, v236, 41
	v_readlane_b32 s5, v236, 42
	global_load_ushort v67, v[120:121], off
	global_load_ushort v163, v[120:121], off offset:1024
	v_lshl_add_u64 v[120:121], s[4:5], 0, v[2:3]
	v_readlane_b32 s4, v236, 43
	v_readlane_b32 s5, v236, 44
	global_load_ushort v70, v[120:121], off
	global_load_ushort v165, v[120:121], off offset:1024
	v_lshl_add_u64 v[120:121], s[4:5], 0, v[2:3]
	v_readlane_b32 s4, v236, 45
	v_readlane_b32 s5, v236, 46
	global_load_ushort v75, v[120:121], off
	global_load_ushort v162, v[120:121], off offset:1024
	v_lshl_add_u64 v[120:121], s[4:5], 0, v[2:3]
	v_readlane_b32 s4, v236, 47
	v_readlane_b32 s5, v236, 48
	global_load_ushort v82, v[120:121], off
	global_load_ushort v161, v[120:121], off offset:1024
	v_lshl_add_u64 v[120:121], s[4:5], 0, v[2:3]
	v_readlane_b32 s4, v236, 49
	v_readlane_b32 s5, v236, 50
	global_load_ushort v87, v[120:121], off
	global_load_ushort v159, v[120:121], off offset:1024
	v_lshl_add_u64 v[120:121], s[4:5], 0, v[2:3]
	global_load_ushort v92, v[120:121], off
	global_load_ushort v160, v[120:121], off offset:1024
	v_lshl_add_u64 v[120:121], s[2:3], 0, v[2:3]
	global_load_ushort v97, v[120:121], off
	global_load_ushort v158, v[120:121], off offset:1024
	v_lshl_add_u64 v[120:121], s[0:1], 0, v[2:3]
	global_load_ushort v103, v[120:121], off
	global_load_ushort v157, v[120:121], off offset:1024
	v_lshl_add_u64 v[120:121], s[6:7], 0, v[2:3]
	global_load_ushort v109, v[120:121], off
	global_load_ushort v155, v[120:121], off offset:1024
	v_lshl_add_u64 v[120:121], s[8:9], 0, v[2:3]
	global_load_ushort v115, v[120:121], off
	global_load_ushort v156, v[120:121], off offset:1024
	s_nop 0
	global_load_ushort v120, v[122:123], off
	global_load_ushort v154, v[122:123], off offset:1024
	v_lshl_add_u64 v[122:123], s[12:13], 0, v[2:3]
	global_load_ushort v121, v[122:123], off
	global_load_ushort v153, v[122:123], off offset:1024
	s_nop 0
	global_load_ushort v122, v[124:125], off
	global_load_ushort v151, v[124:125], off offset:1024
	v_lshl_add_u64 v[124:125], s[20:21], 0, v[2:3]
	global_load_ushort v123, v[124:125], off
	global_load_ushort v152, v[124:125], off offset:1024
	v_lshl_add_u64 v[126:127], s[22:23], 0, v[2:3]
	global_load_ushort v124, v[126:127], off
	global_load_ushort v150, v[126:127], off offset:1024
	v_lshl_add_u64 v[126:127], s[24:25], 0, v[2:3]
	v_lshl_add_u64 v[128:129], s[26:27], 0, v[2:3]
	global_load_ushort v125, v[126:127], off
	global_load_ushort v149, v[126:127], off offset:1024
	s_nop 0
	global_load_ushort v126, v[128:129], off
	global_load_ushort v147, v[128:129], off offset:1024
	v_lshl_add_u64 v[128:129], s[28:29], 0, v[2:3]
	v_lshl_add_u64 v[130:131], s[30:31], 0, v[2:3]
	global_load_ushort v127, v[128:129], off
	global_load_ushort v148, v[128:129], off offset:1024
	s_nop 0
	global_load_ushort v128, v[130:131], off
	global_load_ushort v146, v[130:131], off offset:1024
	v_lshl_add_u64 v[130:131], s[34:35], 0, v[2:3]
	v_lshl_add_u64 v[132:133], s[36:37], 0, v[2:3]
	global_load_ushort v129, v[130:131], off
	global_load_ushort v145, v[130:131], off offset:1024
	s_nop 0
	global_load_ushort v130, v[132:133], off
	global_load_ushort v143, v[132:133], off offset:1024
	v_lshl_add_u64 v[132:133], s[38:39], 0, v[2:3]
	v_lshl_add_u64 v[134:135], s[40:41], 0, v[2:3]
	global_load_ushort v131, v[132:133], off
	global_load_ushort v144, v[132:133], off offset:1024
	s_nop 0
	global_load_ushort v132, v[134:135], off
	global_load_ushort v142, v[134:135], off offset:1024
	v_lshl_add_u64 v[134:135], s[42:43], 0, v[2:3]
	global_load_ushort v140, v[134:135], off
	global_load_ushort v141, v[134:135], off offset:1024
	v_lshl_add_u64 v[134:135], s[44:45], 0, v[2:3]
	global_load_ushort v136, v[134:135], off
	global_load_ushort v138, v[134:135], off offset:1024
	v_lshl_add_u64 v[134:135], s[46:47], 0, v[2:3]
	v_lshl_add_u64 v[168:169], s[48:49], 0, v[2:3]
	v_lshl_add_u64 v[2:3], s[50:51], 0, v[2:3]
	global_load_ushort v137, v[134:135], off
	global_load_ushort v139, v[134:135], off offset:1024
	s_nop 0
	global_load_ushort v134, v[168:169], off
	global_load_ushort v135, v[168:169], off offset:1024
	global_load_ushort v76, v[2:3], off
	global_load_ushort v133, v[2:3], off offset:1024
	s_waitcnt vmcnt(0)
	v_lshlrev_b32_e32 v3, 16, v173
	v_mul_f32_e32 v3, 0xbfb8aa3b, v3
	v_exp_f32_e32 v3, v3
	v_lshlrev_b32_e32 v2, 16, v167
	v_cmp_ne_u32_e64 s[4:5], 1, v4
	s_andn2_b64 vcc, exec, s[68:69]
	v_add_f32_e32 v3, 1.0, v3
	v_rcp_f32_e32 v3, v3
	s_nop 0
	v_mul_f32_e32 v2, v3, v2
	s_cbranch_vccnz .LBB0_454
	v_readlane_b32 vcc_lo, v236, 51
	v_readlane_b32 vcc_hi, v236, 52
	s_nop 1
	v_lshl_add_u64 v[168:169], v[18:19], 2, vcc
	global_store_dword v[168:169], v2, off

.LBB0_513:
	ds_read_b128 v[38:41], v23
	ds_read_b128 v[42:45], v23 offset:16
	v_add_u32_e32 v48, 4, v37
	v_add_u32_e32 v46, s2, v37
	v_cmp_lt_u32_e32 vcc, 27, v37
	v_mov_b32_e32 v37, v48
	s_waitcnt lgkmcnt(1)
	v_add_f32_e32 v48, 0, v38
	v_add_f32_e32 v48, v48, v39
	v_add_f32_e32 v48, v48, v40
	v_add_f32_e32 v48, v48, v41
	s_waitcnt lgkmcnt(0)
	v_add_f32_e32 v48, v48, v42
	v_add_f32_e32 v48, v48, v43
	v_add_f32_e32 v48, v48, v44
	v_add_f32_e32 v48, v48, v45
	ds_bpermute_b32 v49, v18, v48
	global_load_dwordx4 v[2:5], v[24:25], off offset:16
	global_load_dwordx4 v[10:13], v[24:25], off
	global_load_dwordx4 v[6:9], v[26:27], off offset:16
	global_load_dwordx4 v[14:17], v[26:27], off
	s_mov_b32 s3, 0x800000
	s_or_b64 s[0:1], vcc, s[0:1]
	v_ashrrev_i32_e32 v47, 31, v46
	s_waitcnt lgkmcnt(0)
	v_add_f32_e32 v48, v48, v49
	ds_bpermute_b32 v49, v32, v48
	v_lshlrev_b64 v[46:47], 10, v[46:47]
	v_add_u32_e32 v23, 0x2000, v23
	v_lshl_add_u64 v[46:47], v[20:21], 0, v[46:47]
	s_waitcnt lgkmcnt(0)
	v_add_f32_e32 v48, v48, v49
	ds_bpermute_b32 v49, v33, v48
	s_waitcnt lgkmcnt(0)
	v_add_f32_e32 v48, v48, v49
	ds_bpermute_b32 v49, v34, v48
	s_waitcnt lgkmcnt(0)
	v_add_f32_e32 v48, v48, v49
	ds_bpermute_b32 v49, v35, v48
	s_waitcnt lgkmcnt(0)
	v_add_f32_e32 v48, v48, v49
	ds_bpermute_b32 v49, v36, v48
	s_waitcnt lgkmcnt(0)
	v_add_f32_e32 v48, v48, v49
	v_mul_f32_e32 v48, 0x3b000000, v48
	v_pk_add_f32 v[38:39], v[38:39], v[48:49] op_sel_hi:[1,0] neg_lo:[0,1] neg_hi:[0,1]
	v_pk_add_f32 v[40:41], v[40:41], v[48:49] op_sel_hi:[1,0] neg_lo:[0,1] neg_hi:[0,1]
	v_pk_add_f32 v[42:43], v[42:43], v[48:49] op_sel_hi:[1,0] neg_lo:[0,1] neg_hi:[0,1]
	v_pk_add_f32 v[44:45], v[44:45], v[48:49] op_sel_hi:[1,0] neg_lo:[0,1] neg_hi:[0,1]
	v_pk_mul_f32 v[48:49], v[38:39], v[38:39]
	v_pk_mul_f32 v[50:51], v[40:41], v[40:41]
	v_add_f32_e32 v48, v48, v49
	v_add_f32_e32 v48, v50, v48
	v_pk_mul_f32 v[52:53], v[42:43], v[42:43]
	v_add_f32_e32 v48, v51, v48
	v_add_f32_e32 v48, v52, v48
	v_pk_mul_f32 v[54:55], v[44:45], v[44:45]
	v_add_f32_e32 v48, v53, v48
	v_add_f32_e32 v48, v54, v48
	v_add_f32_e32 v48, v55, v48
	ds_bpermute_b32 v49, v18, v48
	s_waitcnt lgkmcnt(0)
	v_add_f32_e32 v48, v48, v49
	ds_bpermute_b32 v49, v32, v48
	s_waitcnt lgkmcnt(0)
	v_add_f32_e32 v48, v48, v49
	ds_bpermute_b32 v49, v33, v48
	s_waitcnt lgkmcnt(0)
	v_add_f32_e32 v48, v48, v49
	ds_bpermute_b32 v49, v34, v48
	s_waitcnt lgkmcnt(0)
	v_add_f32_e32 v48, v48, v49
	ds_bpermute_b32 v49, v35, v48
	s_waitcnt lgkmcnt(0)
	v_add_f32_e32 v48, v48, v49
	ds_bpermute_b32 v49, v36, v48
	s_waitcnt lgkmcnt(0)
	v_add_f32_e32 v48, v48, v49
	v_fmamk_f32 v48, v48, 0x3b000000, v30
	v_mul_f32_e32 v49, 0x4b800000, v48
	v_cmp_gt_f32_e32 vcc, s3, v48
	s_nop 1
	v_cndmask_b32_e32 v48, v48, v49, vcc
	v_rsq_f32_e32 v48, v48
	s_nop 0
	v_mul_f32_e32 v49, 0x45800000, v48
	v_cndmask_b32_e32 v48, v48, v49, vcc
	v_pk_mul_f32 v[38:39], v[38:39], v[48:49] op_sel_hi:[1,0]
	v_pk_mul_f32 v[40:41], v[40:41], v[48:49] op_sel_hi:[1,0]
	v_pk_mul_f32 v[42:43], v[42:43], v[48:49] op_sel_hi:[1,0]
	v_pk_mul_f32 v[44:45], v[44:45], v[48:49] op_sel_hi:[1,0]
	s_waitcnt vmcnt(0)
	v_pk_fma_f32 v[10:11], v[10:11], v[38:39], v[14:15]
	v_pk_fma_f32 v[12:13], v[12:13], v[40:41], v[16:17]
	v_pk_fma_f32 v[2:3], v[2:3], v[42:43], v[6:7]
	v_pk_fma_f32 v[4:5], v[4:5], v[44:45], v[8:9]
	v_mul_f32_e32 v6, 0xbfb8aa3b, v10
	v_mul_f32_e32 v7, 0xbfb8aa3b, v11
	v_mul_f32_e32 v8, 0xbfb8aa3b, v12
	v_mul_f32_e32 v9, 0xbfb8aa3b, v13
	v_mul_f32_e32 v14, 0xbfb8aa3b, v2
	v_mul_f32_e32 v15, 0xbfb8aa3b, v3
	v_mul_f32_e32 v16, 0xbfb8aa3b, v4
	v_mul_f32_e32 v17, 0xbfb8aa3b, v5
	v_exp_f32_e32 v6, v6
	v_exp_f32_e32 v7, v7
	v_exp_f32_e32 v8, v8
	v_exp_f32_e32 v9, v9
	v_exp_f32_e32 v14, v14
	v_exp_f32_e32 v15, v15
	v_exp_f32_e32 v16, v16
	v_exp_f32_e32 v17, v17
	v_add_f32_e32 v6, 1.0, v6
	v_add_f32_e32 v7, 1.0, v7
	v_add_f32_e32 v8, 1.0, v8
	v_add_f32_e32 v9, 1.0, v9
	v_add_f32_e32 v14, 1.0, v14
	v_add_f32_e32 v15, 1.0, v15
	v_add_f32_e32 v16, 1.0, v16
	v_add_f32_e32 v17, 1.0, v17
	v_rcp_f32_e32 v6, v6
	v_rcp_f32_e32 v7, v7
	v_rcp_f32_e32 v8, v8
	v_rcp_f32_e32 v9, v9
	v_rcp_f32_e32 v14, v14
	v_rcp_f32_e32 v15, v15
	v_rcp_f32_e32 v16, v16
	v_rcp_f32_e32 v17, v17
	v_pk_mul_f32 v[6:7], v[10:11], v[6:7]
	v_pk_mul_f32 v[8:9], v[12:13], v[8:9]
	v_pk_mul_f32 v[10:11], v[2:3], v[14:15]
	v_pk_mul_f32 v[12:13], v[4:5], v[16:17]
	v_cvt_pk_bf16_f32 v2, v6, v7
	v_cvt_pk_bf16_f32 v3, v8, v9
	v_cvt_pk_bf16_f32 v4, v10, v11
	v_cvt_pk_bf16_f32 v5, v12, v13
	global_store_dwordx4 v[46:47], v[2:5], off
	s_andn2_b64 exec, exec, s[0:1]
	s_cbranch_execnz .LBB0_513
	s_or_b64 exec, exec, s[0:1]
	v_readlane_b32 s0, v235, 8
	v_readlane_b32 s1, v235, 12
	s_add_i32 s1, s1, s0
	s_add_i32 s4, s4, s0
	v_readlane_b32 s52, v236, 3
	s_cmpk_gt_i32 s1, 0x1ff
	v_readlane_b32 s53, v236, 4
	s_cbranch_scc0 .LBB0_450

.LBB0_519:
	v_cndmask_b32_e64 v2, 0, 1, s[92:93]
	v_add_u32_e32 v18, s4, v0
	v_cmp_ne_u32_e64 s[6:7], 1, v2
	v_lshlrev_b64 v[2:3], 2, v[18:19]
	v_lshl_add_u64 v[4:5], s[90:91], 0, v[2:3]
	v_add_co_u32_e32 v6, vcc, 0x1000, v4
	global_load_dword v24, v[4:5], off
	s_waitcnt vmcnt(0)
	global_load_dword v61, v[4:5], off offset:2048
	v_addc_co_u32_e32 v7, vcc, 0, v5, vcc
	global_load_dword v60, v[6:7], off
	global_load_dword v58, v[6:7], off offset:2048
	v_add_co_u32_e32 v6, vcc, 0x2000, v4
	s_mov_b32 s5, 0xf000
	s_nop 0
	v_addc_co_u32_e32 v7, vcc, 0, v5, vcc
	global_load_dword v57, v[6:7], off
	global_load_dword v54, v[6:7], off offset:2048
	v_add_co_u32_e32 v6, vcc, 0x3000, v4
	s_nop 1
	v_addc_co_u32_e32 v7, vcc, 0, v5, vcc
	global_load_dword v56, v[6:7], off
	global_load_dword v52, v[6:7], off offset:2048
	v_add_co_u32_e32 v6, vcc, s0, v4
	s_nop 1
	v_addc_co_u32_e32 v7, vcc, 0, v5, vcc
	global_load_dword v51, v[6:7], off
	global_load_dword v50, v[6:7], off offset:2048
	v_add_co_u32_e32 v6, vcc, 0x5000, v4
	s_nop 1
	v_addc_co_u32_e32 v7, vcc, 0, v5, vcc
	global_load_dword v49, v[6:7], off
	global_load_dword v48, v[6:7], off offset:2048
	v_add_co_u32_e32 v6, vcc, 0x6000, v4
	s_nop 1
	v_addc_co_u32_e32 v7, vcc, 0, v5, vcc
	global_load_dword v47, v[6:7], off
	global_load_dword v45, v[6:7], off offset:2048
	v_add_co_u32_e32 v6, vcc, 0x7000, v4
	s_nop 1
	v_addc_co_u32_e32 v7, vcc, 0, v5, vcc
	global_load_dword v46, v[6:7], off
	global_load_dword v44, v[6:7], off offset:2048
	v_add_co_u32_e32 v6, vcc, 0x8000, v4
	s_nop 1
	v_addc_co_u32_e32 v7, vcc, 0, v5, vcc
	global_load_dword v43, v[6:7], off
	global_load_dword v42, v[6:7], off offset:2048
	v_add_co_u32_e32 v6, vcc, 0x9000, v4
	s_nop 1
	v_addc_co_u32_e32 v7, vcc, 0, v5, vcc
	global_load_dword v41, v[6:7], off
	global_load_dword v40, v[6:7], off offset:2048
	v_add_co_u32_e32 v6, vcc, 0xa000, v4
	s_nop 1
	v_addc_co_u32_e32 v7, vcc, 0, v5, vcc
	global_load_dword v39, v[6:7], off
	global_load_dword v26, v[6:7], off offset:2048
	v_add_co_u32_e32 v6, vcc, 0xb000, v4
	s_nop 1
	v_addc_co_u32_e32 v7, vcc, 0, v5, vcc
	global_load_dword v27, v[6:7], off
	global_load_dword v25, v[6:7], off offset:2048
	v_add_co_u32_e32 v6, vcc, 0xc000, v4
	s_nop 1
	v_addc_co_u32_e32 v7, vcc, 0, v5, vcc
	global_load_dword v23, v[6:7], off
	global_load_dword v14, v[6:7], off offset:2048
	v_add_co_u32_e32 v6, vcc, 0xd000, v4
	s_nop 1
	v_addc_co_u32_e32 v7, vcc, 0, v5, vcc
	global_load_dword v10, v[6:7], off
	global_load_dword v9, v[6:7], off offset:2048
	v_add_co_u32_e32 v6, vcc, s1, v4
	s_nop 1
	v_addc_co_u32_e32 v7, vcc, 0, v5, vcc
	v_add_co_u32_e32 v4, vcc, s5, v4
	global_load_dword v8, v[6:7], off
	s_nop 0
	global_load_dword v7, v[6:7], off offset:2048
	v_addc_co_u32_e32 v5, vcc, 0, v5, vcc
	global_load_dword v6, v[4:5], off
	v_lshl_add_u64 v[4:5], s[86:87], 0, v[2:3]
	s_movk_i32 s5, 0x1000
	v_add_co_u32_e32 v12, vcc, s5, v4
	s_movk_i32 s5, 0x2000
	s_nop 0
	v_addc_co_u32_e32 v13, vcc, 0, v5, vcc
	v_add_co_u32_e32 v16, vcc, s5, v4
	s_movk_i32 s5, 0x3000
	s_nop 0
	v_addc_co_u32_e32 v17, vcc, 0, v5, vcc
	global_load_dword v11, v[4:5], off
	global_load_dword v15, v[4:5], off offset:2048
	global_load_dword v65, v[16:17], off offset:-4096
	global_load_dword v66, v[12:13], off offset:2048
	global_load_dword v67, v[16:17], off
	global_load_dword v68, v[16:17], off offset:2048
	v_add_co_u32_e32 v12, vcc, s5, v4
	s_movk_i32 s5, 0x5000
	s_nop 0
	v_addc_co_u32_e32 v13, vcc, 0, v5, vcc
	v_add_co_u32_e32 v16, vcc, s0, v4
	s_waitcnt vmcnt(0) lgkmcnt(0)
	v_fma_f32 v11, v24, v11, 0
	v_addc_co_u32_e32 v17, vcc, 0, v5, vcc
	global_load_dword v69, v[16:17], off offset:-4096
	global_load_dword v70, v[12:13], off offset:2048
	global_load_dword v71, v[16:17], off
	global_load_dword v72, v[16:17], off offset:2048
	v_add_co_u32_e32 v12, vcc, s5, v4
	s_movk_i32 s5, 0x6000
	s_nop 0
	v_addc_co_u32_e32 v13, vcc, 0, v5, vcc
	v_add_co_u32_e32 v16, vcc, s5, v4
	s_movk_i32 s5, 0x7000
	s_nop 0
	v_addc_co_u32_e32 v17, vcc, 0, v5, vcc
	global_load_dword v73, v[16:17], off offset:-4096
	global_load_dword v74, v[12:13], off offset:2048
	global_load_dword v75, v[16:17], off
	global_load_dword v76, v[16:17], off offset:2048
	v_add_co_u32_e32 v12, vcc, s5, v4
	s_mov_b32 s5, 0x8000
	s_nop 0
	v_addc_co_u32_e32 v13, vcc, 0, v5, vcc
	v_add_co_u32_e32 v16, vcc, s5, v4
	s_mov_b32 s5, 0x9000
	s_nop 0
	v_addc_co_u32_e32 v17, vcc, 0, v5, vcc
	global_load_dword v77, v[16:17], off offset:-4096
	global_load_dword v78, v[12:13], off offset:2048
	global_load_dword v79, v[16:17], off
	global_load_dword v80, v[16:17], off offset:2048
	v_add_co_u32_e32 v12, vcc, s5, v4
	s_mov_b32 s5, 0xa000
	s_nop 0
	v_addc_co_u32_e32 v13, vcc, 0, v5, vcc
	v_add_co_u32_e32 v16, vcc, s5, v4
	s_mov_b32 s5, 0xb000
	s_nop 0
	v_addc_co_u32_e32 v17, vcc, 0, v5, vcc
	global_load_dword v81, v[16:17], off offset:-4096
	global_load_dword v82, v[12:13], off offset:2048
	global_load_dword v83, v[16:17], off
	global_load_dword v84, v[16:17], off offset:2048
	v_add_co_u32_e32 v12, vcc, s5, v4
	s_mov_b32 s5, 0xc000
	s_nop 0
	v_addc_co_u32_e32 v13, vcc, 0, v5, vcc
	v_add_co_u32_e32 v16, vcc, s5, v4
	s_mov_b32 s5, 0xd000
	s_nop 0
	v_addc_co_u32_e32 v17, vcc, 0, v5, vcc
	global_load_dword v85, v[16:17], off offset:-4096
	global_load_dword v86, v[12:13], off offset:2048
	global_load_dword v87, v[16:17], off
	global_load_dword v88, v[16:17], off offset:2048
	v_add_co_u32_e32 v12, vcc, s5, v4
	v_fmac_f32_e32 v11, v61, v15
	s_nop 0
	v_addc_co_u32_e32 v13, vcc, 0, v5, vcc
	v_add_co_u32_e32 v4, vcc, s1, v4
	v_fmac_f32_e32 v11, v60, v65
	s_nop 0
	v_addc_co_u32_e32 v5, vcc, 0, v5, vcc
	global_load_dword v89, v[4:5], off offset:-4096
	global_load_dword v90, v[12:13], off offset:2048
	global_load_dword v64, v[4:5], off
	global_load_dword v62, v[4:5], off offset:2048
	v_lshlrev_b64 v[4:5], 1, v[18:19]
	v_lshl_add_u64 v[12:13], s[68:69], 0, v[4:5]
	global_load_ushort v63, v[12:13], off
	global_load_ushort v59, v[12:13], off offset:1024
	v_lshl_add_u64 v[12:13], s[72:73], 0, v[4:5]
	global_load_ushort v55, v[12:13], off
	global_load_ushort v53, v[12:13], off offset:1024
	v_fma_f32 v12, v24, v15, 0
	v_fmac_f32_e32 v12, v61, v65
	v_fma_f32 v13, v24, v65, 0
	v_fmac_f32_e32 v11, v58, v66
	v_fmac_f32_e32 v12, v60, v66
	v_fmac_f32_e32 v13, v61, v66
	v_fma_f32 v15, v24, v66, 0
	v_fmac_f32_e32 v11, v57, v67
	v_fmac_f32_e32 v12, v58, v67
	v_fmac_f32_e32 v13, v60, v67
	v_fmac_f32_e32 v15, v61, v67
	v_fma_f32 v16, v24, v67, 0
	v_fmac_f32_e32 v11, v54, v68
	v_fmac_f32_e32 v12, v57, v68
	v_fmac_f32_e32 v13, v58, v68
	v_fmac_f32_e32 v15, v60, v68
	v_fmac_f32_e32 v16, v61, v68
	v_fma_f32 v17, v24, v68, 0
	s_waitcnt vmcnt(27)
	v_fmac_f32_e32 v11, v56, v69
	v_fmac_f32_e32 v12, v54, v69
	v_fmac_f32_e32 v13, v57, v69
	v_fmac_f32_e32 v15, v58, v69
	v_fmac_f32_e32 v16, v60, v69
	v_fmac_f32_e32 v17, v61, v69
	v_fma_f32 v18, v24, v69, 0
	s_waitcnt vmcnt(26)
	v_fmac_f32_e32 v11, v52, v70
	v_fmac_f32_e32 v12, v56, v70
	v_fmac_f32_e32 v13, v54, v70
	v_fmac_f32_e32 v15, v57, v70
	v_fmac_f32_e32 v16, v58, v70
	v_fmac_f32_e32 v17, v60, v70
	v_fmac_f32_e32 v18, v61, v70
	v_fma_f32 v24, v24, v70, 0
	s_waitcnt vmcnt(25)
	v_fmac_f32_e32 v11, v51, v71
	v_fmac_f32_e32 v12, v52, v71
	v_fmac_f32_e32 v13, v56, v71
	v_fmac_f32_e32 v15, v54, v71
	v_fmac_f32_e32 v16, v57, v71
	v_fmac_f32_e32 v17, v58, v71
	v_fmac_f32_e32 v18, v60, v71
	v_fmac_f32_e32 v24, v61, v71
	s_waitcnt vmcnt(24)
	v_fmac_f32_e32 v11, v50, v72
	v_fmac_f32_e32 v12, v51, v72
	v_fmac_f32_e32 v13, v52, v72
	v_fmac_f32_e32 v15, v56, v72
	v_fmac_f32_e32 v16, v54, v72
	v_fmac_f32_e32 v17, v57, v72
	v_fmac_f32_e32 v18, v58, v72
	v_fmac_f32_e32 v24, v60, v72
	s_waitcnt vmcnt(23)
	v_fmac_f32_e32 v11, v49, v73
	v_fmac_f32_e32 v12, v50, v73
	v_fmac_f32_e32 v13, v51, v73
	v_fmac_f32_e32 v15, v52, v73
	v_fmac_f32_e32 v16, v56, v73
	v_fmac_f32_e32 v17, v54, v73
	v_fmac_f32_e32 v18, v57, v73
	v_fmac_f32_e32 v24, v58, v73
	v_lshl_add_u64 v[60:61], s[24:25], 0, v[2:3]
	s_waitcnt vmcnt(22)
	v_fmac_f32_e32 v11, v48, v74
	v_fmac_f32_e32 v12, v49, v74
	v_fmac_f32_e32 v13, v50, v74
	v_fmac_f32_e32 v15, v51, v74
	v_fmac_f32_e32 v16, v52, v74
	v_fmac_f32_e32 v17, v56, v74
	v_fmac_f32_e32 v18, v54, v74
	v_fmac_f32_e32 v24, v57, v74
	global_store_dword v[60:61], v73, off
	v_lshl_add_u64 v[60:61], s[26:27], 0, v[2:3]
	s_waitcnt vmcnt(22)
	v_fmac_f32_e32 v11, v47, v75
	v_fmac_f32_e32 v12, v48, v75
	v_fmac_f32_e32 v13, v49, v75
	v_fmac_f32_e32 v15, v50, v75
	v_fmac_f32_e32 v16, v51, v75
	v_fmac_f32_e32 v17, v52, v75
	v_fmac_f32_e32 v18, v56, v75
	v_fmac_f32_e32 v24, v54, v75
	v_lshl_add_u64 v[66:67], s[20:21], 0, v[2:3]
	global_store_dword v[60:61], v74, off
	v_lshl_add_u64 v[60:61], s[28:29], 0, v[2:3]
	s_waitcnt vmcnt(22)
	v_fmac_f32_e32 v11, v45, v76
	v_fmac_f32_e32 v12, v47, v76
	v_fmac_f32_e32 v13, v48, v76
	v_fmac_f32_e32 v15, v49, v76
	v_fmac_f32_e32 v16, v50, v76
	v_fmac_f32_e32 v17, v51, v76
	v_fmac_f32_e32 v18, v52, v76
	v_fmac_f32_e32 v24, v56, v76
	v_lshl_add_u64 v[56:57], s[34:35], 0, v[2:3]
	global_store_dword v[66:67], v71, off
	v_lshl_add_u64 v[66:67], s[22:23], 0, v[2:3]
	global_store_dword v[60:61], v75, off
	v_lshl_add_u64 v[60:61], s[30:31], 0, v[2:3]
	s_waitcnt vmcnt(23)
	global_store_dword v[56:57], v77, off
	v_fmac_f32_e32 v11, v46, v77
	v_fmac_f32_e32 v12, v45, v77
	v_fmac_f32_e32 v13, v47, v77
	v_fmac_f32_e32 v15, v48, v77
	v_fmac_f32_e32 v16, v49, v77
	v_fmac_f32_e32 v17, v50, v77
	v_fmac_f32_e32 v18, v51, v77
	v_fmac_f32_e32 v24, v52, v77
	v_lshl_add_u64 v[56:57], s[36:37], 0, v[2:3]
	global_store_dword v[66:67], v72, off
	global_store_dword v[60:61], v76, off
	s_waitcnt vmcnt(25)
	global_store_dword v[56:57], v78, off
	v_fmac_f32_e32 v11, v44, v78
	v_fmac_f32_e32 v12, v46, v78
	v_fmac_f32_e32 v13, v45, v78
	v_fmac_f32_e32 v15, v47, v78
	v_fmac_f32_e32 v16, v48, v78
	v_fmac_f32_e32 v17, v49, v78
	v_fmac_f32_e32 v18, v50, v78
	v_fmac_f32_e32 v24, v51, v78
	v_lshl_add_u64 v[56:57], s[94:95], 0, v[4:5]
	global_load_ushort v65, v[56:57], off
	global_load_ushort v66, v[56:57], off offset:1024
	v_lshl_add_u64 v[56:57], s[96:97], 0, v[4:5]
	global_load_ushort v67, v[56:57], off
	global_load_ushort v68, v[56:57], off offset:1024
	v_lshl_add_u64 v[56:57], s[2:3], 0, v[4:5]
	v_lshl_add_u64 v[60:61], s[12:13], 0, v[4:5]
	global_load_ushort v58, v[56:57], off
	s_nop 0
	global_load_ushort v57, v[56:57], off offset:1024
	s_nop 0
	global_load_ushort v56, v[60:61], off
	global_load_ushort v54, v[60:61], off offset:1024
	v_lshl_add_u64 v[60:61], s[16:17], 0, v[4:5]
	global_load_ushort v52, v[60:61], off
	global_load_ushort v51, v[60:61], off offset:1024
	v_lshl_add_u64 v[60:61], s[18:19], 0, v[4:5]
	global_load_ushort v5, v[60:61], off
	global_load_ushort v4, v[60:61], off offset:1024
	s_waitcnt vmcnt(37)
	v_fmac_f32_e32 v24, v50, v79
	v_fmac_f32_e32 v18, v49, v79
	s_waitcnt vmcnt(36)
	v_fmac_f32_e32 v24, v49, v80
	v_fmac_f32_e32 v17, v48, v79
	v_fmac_f32_e32 v18, v48, v80
	s_waitcnt vmcnt(35)
	v_fmac_f32_e32 v24, v48, v81
	v_fmac_f32_e32 v16, v47, v79
	v_fmac_f32_e32 v17, v47, v80
	v_fmac_f32_e32 v18, v47, v81
	s_waitcnt vmcnt(34)
	v_fmac_f32_e32 v24, v47, v82
	v_fmac_f32_e32 v15, v45, v79
	v_fmac_f32_e32 v16, v45, v80
	v_fmac_f32_e32 v17, v45, v81
	v_fmac_f32_e32 v18, v45, v82
	s_waitcnt vmcnt(33)
	v_fmac_f32_e32 v24, v45, v83
	v_fmac_f32_e32 v13, v46, v79
	v_fmac_f32_e32 v15, v46, v80
	v_fmac_f32_e32 v16, v46, v81
	v_fmac_f32_e32 v17, v46, v82
	v_fmac_f32_e32 v18, v46, v83
	s_waitcnt vmcnt(32)
	v_fmac_f32_e32 v24, v46, v84
	v_fmac_f32_e32 v12, v44, v79
	v_fmac_f32_e32 v13, v44, v80
	v_fmac_f32_e32 v15, v44, v81
	v_fmac_f32_e32 v16, v44, v82
	v_fmac_f32_e32 v17, v44, v83
	v_fmac_f32_e32 v18, v44, v84
	s_waitcnt vmcnt(31)
	v_fmac_f32_e32 v24, v44, v85
	v_fmac_f32_e32 v11, v43, v79
	v_fmac_f32_e32 v12, v43, v80
	v_fmac_f32_e32 v13, v43, v81
	v_fmac_f32_e32 v15, v43, v82
	v_fmac_f32_e32 v16, v43, v83
	v_fmac_f32_e32 v17, v43, v84
	v_fmac_f32_e32 v18, v43, v85
	s_waitcnt vmcnt(30)
	v_fmac_f32_e32 v24, v43, v86
	v_fmac_f32_e32 v11, v42, v80
	v_fmac_f32_e32 v12, v42, v81
	v_fmac_f32_e32 v13, v42, v82
	v_fmac_f32_e32 v15, v42, v83
	v_fmac_f32_e32 v16, v42, v84
	v_fmac_f32_e32 v17, v42, v85
	v_fmac_f32_e32 v18, v42, v86
	s_waitcnt vmcnt(29)
	v_fmac_f32_e32 v24, v42, v87
	v_fmac_f32_e32 v11, v41, v81
	v_fmac_f32_e32 v12, v41, v82
	v_fmac_f32_e32 v13, v41, v83
	v_fmac_f32_e32 v15, v41, v84
	v_fmac_f32_e32 v16, v41, v85
	v_fmac_f32_e32 v17, v41, v86
	v_fmac_f32_e32 v18, v41, v87
	s_waitcnt vmcnt(28)
	v_fmac_f32_e32 v24, v41, v88
	v_fmac_f32_e32 v11, v40, v82
	v_fmac_f32_e32 v12, v40, v83
	v_fmac_f32_e32 v13, v40, v84
	v_fmac_f32_e32 v15, v40, v85
	v_fmac_f32_e32 v16, v40, v86
	v_fmac_f32_e32 v17, v40, v87
	v_fmac_f32_e32 v18, v40, v88
	s_waitcnt vmcnt(27)
	v_fmac_f32_e32 v24, v40, v89
	v_fmac_f32_e32 v11, v39, v83
	v_fmac_f32_e32 v12, v39, v84
	v_fmac_f32_e32 v13, v39, v85
	v_fmac_f32_e32 v15, v39, v86
	v_fmac_f32_e32 v16, v39, v87
	v_fmac_f32_e32 v17, v39, v88
	v_fmac_f32_e32 v18, v39, v89
	s_waitcnt vmcnt(26)
	v_fmac_f32_e32 v24, v39, v90
	v_fmac_f32_e32 v11, v26, v84
	v_fmac_f32_e32 v12, v26, v85
	v_fmac_f32_e32 v13, v26, v86
	v_fmac_f32_e32 v15, v26, v87
	v_fmac_f32_e32 v16, v26, v88
	v_fmac_f32_e32 v17, v26, v89
	v_fmac_f32_e32 v18, v26, v90
	s_waitcnt vmcnt(25)
	v_fmac_f32_e32 v24, v26, v64
	v_fmac_f32_e32 v11, v27, v85
	v_fmac_f32_e32 v12, v27, v86
	v_fmac_f32_e32 v13, v27, v87
	v_fmac_f32_e32 v15, v27, v88
	v_fmac_f32_e32 v16, v27, v89
	v_fmac_f32_e32 v17, v27, v90
	v_fmac_f32_e32 v18, v27, v64
	s_waitcnt vmcnt(24)
	v_fmac_f32_e32 v24, v27, v62
	s_waitcnt vmcnt(22)
	v_lshlrev_b32_e32 v27, 16, v59
	v_mul_f32_e32 v27, 0xbfb8aa3b, v27
	v_exp_f32_e32 v27, v27
	v_lshlrev_b32_e32 v26, 16, v63
	v_fmac_f32_e32 v11, v25, v86
	v_fmac_f32_e32 v12, v25, v87
	v_add_f32_e32 v27, 1.0, v27
	v_rcp_f32_e32 v27, v27
	v_fmac_f32_e32 v11, v23, v87
	v_fmac_f32_e32 v12, v23, v88
	v_fmac_f32_e32 v13, v25, v88
	v_mul_f32_e32 v39, v27, v26
	v_lshl_add_u64 v[26:27], s[66:67], 0, v[2:3]
	global_store_dword v[26:27], v39, off
	s_waitcnt vmcnt(21)
	v_lshlrev_b32_e32 v26, 16, v53
	v_mul_f32_e32 v26, 0xbfb8aa3b, v26
	v_exp_f32_e32 v26, v26
	v_fmac_f32_e32 v11, v14, v88
	v_fmac_f32_e32 v12, v14, v89
	v_fmac_f32_e32 v13, v23, v89
	v_add_f32_e32 v26, 1.0, v26
	v_fmac_f32_e32 v15, v25, v89
	v_rcp_f32_e32 v26, v26
	v_fmac_f32_e32 v11, v10, v89
	v_fmac_f32_e32 v12, v10, v90
	v_fmac_f32_e32 v13, v14, v90
	v_fmac_f32_e32 v15, v23, v90
	v_fmac_f32_e32 v16, v25, v90
	v_lshl_add_u64 v[60:61], s[38:39], 0, v[2:3]
	v_lshl_add_u64 v[48:49], s[44:45], 0, v[2:3]
	v_lshl_add_u64 v[40:41], s[60:61], 0, v[2:3]
	v_fmac_f32_e32 v11, v9, v90
	v_fmac_f32_e32 v12, v9, v64
	v_fmac_f32_e32 v13, v10, v64
	v_fmac_f32_e32 v15, v14, v64
	v_fmac_f32_e32 v16, v23, v64
	v_fmac_f32_e32 v17, v25, v64
	global_store_dword v[60:61], v79, off
	v_lshl_add_u64 v[60:61], s[40:41], 0, v[2:3]
	global_store_dword v[48:49], v82, off
	v_lshl_add_u64 v[48:49], s[46:47], 0, v[2:3]
	v_lshl_add_u64 v[44:45], s[52:53], 0, v[2:3]
	v_lshl_add_u64 v[42:43], s[56:57], 0, v[2:3]
	global_store_dword v[40:41], v90, off
	v_lshl_add_u64 v[40:41], s[62:63], 0, v[2:3]
	v_fmac_f32_e32 v11, v8, v64
	v_fmac_f32_e32 v12, v8, v62
	v_fmac_f32_e32 v13, v9, v62
	v_fmac_f32_e32 v15, v10, v62
	v_fmac_f32_e32 v16, v14, v62
	v_fmac_f32_e32 v17, v23, v62
	v_fmac_f32_e32 v18, v25, v62
	v_fmac_f32_e32 v24, v25, v39
	v_lshlrev_b32_e32 v25, 16, v55
	global_store_dword v[60:61], v80, off
	v_lshl_add_u64 v[60:61], s[42:43], 0, v[2:3]
	global_store_dword v[48:49], v83, off
	v_lshl_add_u64 v[48:49], s[48:49], 0, v[2:3]
	v_lshl_add_u64 v[46:47], s[50:51], 0, v[2:3]
	global_store_dword v[44:45], v86, off
	v_lshl_add_u64 v[44:45], s[54:55], 0, v[2:3]
	global_store_dword v[42:43], v88, off
	v_lshl_add_u64 v[42:43], s[58:59], 0, v[2:3]
	global_store_dword v[40:41], v64, off
	v_lshl_add_u64 v[40:41], s[64:65], 0, v[2:3]
	v_fmac_f32_e32 v11, v7, v62
	v_fmac_f32_e32 v12, v7, v39
	v_fmac_f32_e32 v13, v8, v39
	v_fmac_f32_e32 v15, v9, v39
	v_fmac_f32_e32 v16, v10, v39
	v_fmac_f32_e32 v17, v14, v39
	v_fmac_f32_e32 v18, v23, v39
	v_mul_f32_e32 v25, v26, v25
	v_lshl_add_u64 v[26:27], s[70:71], 0, v[2:3]
	global_store_dword v[60:61], v81, off
	global_store_dword v[48:49], v84, off
	global_store_dword v[46:47], v85, off
	global_store_dword v[44:45], v87, off
	global_store_dword v[42:43], v89, off
	global_store_dword v[40:41], v62, off
	v_fmac_f32_e32 v11, v6, v39
	global_store_dword v[26:27], v25, off
	v_fmac_f32_e32 v12, v6, v25
	v_fmac_f32_e32 v13, v7, v25
	v_fmac_f32_e32 v15, v8, v25
	v_fmac_f32_e32 v16, v9, v25
	v_fmac_f32_e32 v17, v10, v25
	v_fmac_f32_e32 v18, v14, v25
	v_fmac_f32_e32 v24, v23, v25
	s_waitcnt vmcnt(26)
	v_lshlrev_b32_e32 v25, 16, v66
	v_mul_f32_e32 v25, 0xbfb8aa3b, v25
	v_exp_f32_e32 v25, v25
	v_lshlrev_b32_e32 v23, 16, v65
	v_lshl_add_u64 v[26:27], s[74:75], 0, v[2:3]
	s_waitcnt vmcnt(16)
	v_lshlrev_b32_e32 v4, 16, v4
	v_add_f32_e32 v25, 1.0, v25
	v_rcp_f32_e32 v25, v25
	v_mul_f32_e32 v4, 0xbfb8aa3b, v4
	v_exp_f32_e32 v4, v4
	v_lshlrev_b32_e32 v5, 16, v5
	v_mul_f32_e32 v23, v25, v23
	global_store_dword v[26:27], v23, off
	v_fmac_f32_e32 v13, v6, v23
	v_fmac_f32_e32 v15, v7, v23
	v_fmac_f32_e32 v16, v8, v23
	v_fmac_f32_e32 v17, v9, v23
	v_fmac_f32_e32 v18, v10, v23
	v_fmac_f32_e32 v24, v14, v23
	v_lshlrev_b32_e32 v23, 16, v68
	v_mul_f32_e32 v23, 0xbfb8aa3b, v23
	v_exp_f32_e32 v23, v23
	v_lshlrev_b32_e32 v14, 16, v67
	v_lshl_add_u64 v[26:27], s[76:77], 0, v[2:3]
	v_add_f32_e32 v4, 1.0, v4
	v_add_f32_e32 v23, 1.0, v23
	v_rcp_f32_e32 v23, v23
	v_rcp_f32_e32 v4, v4
	v_mul_f32_e32 v14, v23, v14
	global_store_dword v[26:27], v14, off
	v_fmac_f32_e32 v15, v6, v14
	v_fmac_f32_e32 v16, v7, v14
	v_fmac_f32_e32 v17, v8, v14
	v_fmac_f32_e32 v18, v9, v14
	v_fmac_f32_e32 v24, v10, v14
	v_lshlrev_b32_e32 v14, 16, v57
	v_mul_f32_e32 v14, 0xbfb8aa3b, v14
	v_exp_f32_e32 v14, v14
	v_lshlrev_b32_e32 v10, 16, v58
	v_lshl_add_u64 v[26:27], s[78:79], 0, v[2:3]
	v_add_f32_e32 v14, 1.0, v14
	v_rcp_f32_e32 v14, v14
	s_nop 0
	v_mul_f32_e32 v10, v14, v10
	global_store_dword v[26:27], v10, off
	v_fmac_f32_e32 v16, v6, v10
	v_fmac_f32_e32 v17, v7, v10
	v_fmac_f32_e32 v18, v8, v10
	v_fmac_f32_e32 v24, v9, v10
	v_lshlrev_b32_e32 v10, 16, v54
	v_mul_f32_e32 v10, 0xbfb8aa3b, v10
	v_exp_f32_e32 v10, v10
	v_lshlrev_b32_e32 v9, 16, v56
	v_lshl_add_u64 v[26:27], s[80:81], 0, v[2:3]
	v_add_f32_e32 v10, 1.0, v10
	v_rcp_f32_e32 v10, v10
	s_nop 0
	v_mul_f32_e32 v9, v10, v9
	global_store_dword v[26:27], v9, off
	v_fmac_f32_e32 v17, v6, v9
	v_fmac_f32_e32 v18, v7, v9
	v_fmac_f32_e32 v24, v8, v9
	v_lshlrev_b32_e32 v9, 16, v51
	v_mul_f32_e32 v9, 0xbfb8aa3b, v9
	v_exp_f32_e32 v9, v9
	v_lshlrev_b32_e32 v8, 16, v52
	v_add_f32_e32 v9, 1.0, v9
	v_rcp_f32_e32 v9, v9
	s_nop 0
	v_mul_f32_e32 v10, v9, v8
	v_lshl_add_u64 v[8:9], s[82:83], 0, v[2:3]
	v_fmac_f32_e32 v24, v7, v10
	v_mul_f32_e32 v7, v4, v5
	v_lshl_add_u64 v[4:5], s[84:85], 0, v[2:3]
	global_store_dword v[8:9], v10, off
	v_fmac_f32_e32 v18, v6, v10
	global_store_dword v[4:5], v7, off
	v_fmac_f32_e32 v24, v6, v7
	v_lshl_add_u64 v[2:3], s[88:89], 0, v[2:3]
	global_load_dword v2, v[2:3], off
	v_lshl_add_u32 v3, s4, 2, v178
	s_movk_i32 s4, 0x100
	s_mov_b64 s[92:93], 0
	s_and_b64 vcc, exec, s[6:7]
	s_waitcnt vmcnt(0) lgkmcnt(0)
	v_add_f32_e32 v4, v11, v2
	v_add_f32_e32 v5, v12, v2
	v_add_f32_e32 v6, v13, v2
	v_add_f32_e32 v7, v15, v2
	v_add_f32_e32 v8, v16, v2
	v_add_f32_e32 v9, v17, v2
	v_add_f32_e32 v10, v18, v2
	v_add_f32_e32 v2, v24, v2
	ds_write2st64_b32 v3, v4, v5 offset1:8
	ds_write2st64_b32 v3, v6, v7 offset0:16 offset1:24
	ds_write2st64_b32 v3, v8, v9 offset0:32 offset1:40
	ds_write2st64_b32 v3, v10, v2 offset0:48 offset1:56
	s_cbranch_vccz .LBB0_519
	s_waitcnt lgkmcnt(0)
	s_barrier
	s_mov_b64 s[0:1], exec
	v_readlane_b32 s2, v236, 13
	v_readlane_b32 s3, v236, 14
	s_and_b64 s[2:3], s[0:1], s[2:3]
	s_mov_b64 exec, s[2:3]
	s_cbranch_execz .LBB0_517
	v_cmp_lt_i32_e32 vcc, v32, v31
	v_mov_b32_e32 v23, v19
	v_lshl_add_u64 v[24:25], s[10:11], 0, v[22:23]
	v_cndmask_b32_e32 v2, v30, v32, vcc
	v_cmp_lt_i32_e32 vcc, v33, v31
	v_lshlrev_b32_e32 v18, 2, v2
	v_lshl_add_u64 v[26:27], s[8:9], 0, v[22:23]
	v_cndmask_b32_e32 v2, v30, v33, vcc
	v_cmp_lt_i32_e32 vcc, v34, v31
	v_lshlrev_b32_e32 v39, 2, v2
	s_mov_b64 s[2:3], 0
	v_cndmask_b32_e32 v2, v30, v34, vcc
	v_cmp_lt_i32_e32 vcc, v35, v31
	v_lshlrev_b32_e32 v40, 2, v2
	v_mov_b32_e32 v23, v28
	v_cndmask_b32_e32 v2, v30, v35, vcc
	v_cmp_lt_i32_e32 vcc, v36, v31
	v_lshlrev_b32_e32 v41, 2, v2
	v_mov_b32_e32 v44, v29
	v_cndmask_b32_e32 v2, v30, v36, vcc
	v_cmp_lt_i32_e32 vcc, v37, v31
	v_lshlrev_b32_e32 v42, 2, v2
	s_nop 0
	v_cndmask_b32_e32 v2, v30, v37, vcc
	v_lshlrev_b32_e32 v43, 2, v2
.LBB0_522:
	ds_read_b128 v[46:49], v23
	ds_read_b128 v[50:53], v23 offset:16
	v_add_u32_e32 v45, s33, v44
	v_add_u32_e32 v54, 0x3ffc, v45
	global_load_dwordx4 v[2:5], v[24:25], off offset:16
	global_load_dwordx4 v[10:13], v[24:25], off
	global_load_dwordx4 v[6:9], v[26:27], off offset:16
	global_load_dwordx4 v[14:17], v[26:27], off
	s_waitcnt lgkmcnt(0)
	v_add_f32_e32 v45, 0, v46
	v_add_f32_e32 v45, v45, v47
	v_add_f32_e32 v45, v45, v48
	v_add_f32_e32 v45, v45, v49
	v_add_f32_e32 v45, v45, v50
	v_add_f32_e32 v45, v45, v51
	v_add_f32_e32 v45, v45, v52
	v_add_f32_e32 v45, v45, v53
	ds_bpermute_b32 v56, v18, v45
	v_add_co_u32_e32 v44, vcc, 4, v44
	s_mov_b32 s6, 0x800000
	s_xor_b64 s[4:5], vcc, -1
	s_waitcnt lgkmcnt(0)
	v_add_f32_e32 v45, v45, v56
	ds_bpermute_b32 v56, v39, v45
	v_ashrrev_i32_e32 v55, 31, v54
	s_and_b64 s[4:5], exec, s[4:5]
	v_lshlrev_b64 v[54:55], 10, v[54:55]
	v_add_u32_e32 v23, 0x2000, v23
	s_waitcnt lgkmcnt(0)
	v_add_f32_e32 v45, v45, v56
	ds_bpermute_b32 v56, v40, v45
	s_or_b64 s[2:3], s[4:5], s[2:3]
	v_lshl_add_u64 v[54:55], v[20:21], 0, v[54:55]
	s_waitcnt lgkmcnt(0)
	v_add_f32_e32 v45, v45, v56
	ds_bpermute_b32 v56, v41, v45
	s_waitcnt lgkmcnt(0)
	v_add_f32_e32 v45, v45, v56
	ds_bpermute_b32 v56, v42, v45
	s_waitcnt lgkmcnt(0)
	v_add_f32_e32 v45, v45, v56
	ds_bpermute_b32 v56, v43, v45
	s_waitcnt lgkmcnt(0)
	v_add_f32_e32 v45, v45, v56
	v_mul_f32_e32 v56, 0x3b000000, v45
	v_pk_add_f32 v[46:47], v[46:47], v[56:57] op_sel_hi:[1,0] neg_lo:[0,1] neg_hi:[0,1]
	v_pk_add_f32 v[48:49], v[48:49], v[56:57] op_sel_hi:[1,0] neg_lo:[0,1] neg_hi:[0,1]
	v_pk_add_f32 v[50:51], v[50:51], v[56:57] op_sel_hi:[1,0] neg_lo:[0,1] neg_hi:[0,1]
	v_pk_add_f32 v[52:53], v[52:53], v[56:57] op_sel_hi:[1,0] neg_lo:[0,1] neg_hi:[0,1]
	v_pk_mul_f32 v[56:57], v[46:47], v[46:47]
	v_pk_mul_f32 v[58:59], v[48:49], v[48:49]
	v_add_f32_e32 v45, v56, v57
	v_add_f32_e32 v45, v58, v45
	v_pk_mul_f32 v[60:61], v[50:51], v[50:51]
	v_add_f32_e32 v45, v59, v45
	v_add_f32_e32 v45, v60, v45
	v_pk_mul_f32 v[62:63], v[52:53], v[52:53]
	v_add_f32_e32 v45, v61, v45
	v_add_f32_e32 v45, v62, v45
	v_add_f32_e32 v45, v63, v45
	ds_bpermute_b32 v56, v18, v45
	s_waitcnt lgkmcnt(0)
	v_add_f32_e32 v45, v45, v56
	ds_bpermute_b32 v56, v39, v45
	s_waitcnt lgkmcnt(0)
	v_add_f32_e32 v45, v45, v56
	ds_bpermute_b32 v56, v40, v45
	s_waitcnt lgkmcnt(0)
	v_add_f32_e32 v45, v45, v56
	ds_bpermute_b32 v56, v41, v45
	s_waitcnt lgkmcnt(0)
	v_add_f32_e32 v45, v45, v56
	ds_bpermute_b32 v56, v42, v45
	s_waitcnt lgkmcnt(0)
	v_add_f32_e32 v45, v45, v56
	ds_bpermute_b32 v56, v43, v45
	s_waitcnt lgkmcnt(0)
	v_add_f32_e32 v45, v45, v56
	v_fmamk_f32 v45, v45, 0x3b000000, v38
	v_mul_f32_e32 v56, 0x4b800000, v45
	v_cmp_gt_f32_e32 vcc, s6, v45
	s_nop 1
	v_cndmask_b32_e32 v45, v45, v56, vcc
	v_rsq_f32_e32 v45, v45
	s_nop 0
	v_mul_f32_e32 v56, 0x45800000, v45
	v_cndmask_b32_e32 v56, v45, v56, vcc
	v_pk_mul_f32 v[46:47], v[46:47], v[56:57] op_sel_hi:[1,0]
	v_pk_mul_f32 v[48:49], v[48:49], v[56:57] op_sel_hi:[1,0]
	v_pk_mul_f32 v[50:51], v[50:51], v[56:57] op_sel_hi:[1,0]
	v_pk_mul_f32 v[52:53], v[52:53], v[56:57] op_sel_hi:[1,0]
	s_waitcnt vmcnt(0)
	v_pk_fma_f32 v[10:11], v[10:11], v[46:47], v[14:15]
	v_pk_fma_f32 v[12:13], v[12:13], v[48:49], v[16:17]
	v_pk_fma_f32 v[2:3], v[2:3], v[50:51], v[6:7]
	v_pk_fma_f32 v[4:5], v[4:5], v[52:53], v[8:9]
	v_mul_f32_e32 v6, 0xbfb8aa3b, v10
	v_mul_f32_e32 v7, 0xbfb8aa3b, v11
	v_mul_f32_e32 v8, 0xbfb8aa3b, v12
	v_mul_f32_e32 v9, 0xbfb8aa3b, v13
	v_mul_f32_e32 v14, 0xbfb8aa3b, v2
	v_mul_f32_e32 v15, 0xbfb8aa3b, v3
	v_mul_f32_e32 v16, 0xbfb8aa3b, v4
	v_mul_f32_e32 v17, 0xbfb8aa3b, v5
	v_exp_f32_e32 v6, v6
	v_exp_f32_e32 v7, v7
	v_exp_f32_e32 v8, v8
	v_exp_f32_e32 v9, v9
	v_exp_f32_e32 v14, v14
	v_exp_f32_e32 v15, v15
	v_exp_f32_e32 v16, v16
	v_exp_f32_e32 v17, v17
	v_add_f32_e32 v6, 1.0, v6
	v_add_f32_e32 v7, 1.0, v7
	v_add_f32_e32 v8, 1.0, v8
	v_add_f32_e32 v9, 1.0, v9
	v_add_f32_e32 v14, 1.0, v14
	v_add_f32_e32 v15, 1.0, v15
	v_add_f32_e32 v16, 1.0, v16
	v_add_f32_e32 v17, 1.0, v17
	v_rcp_f32_e32 v6, v6
	v_rcp_f32_e32 v7, v7
	v_rcp_f32_e32 v8, v8
	v_rcp_f32_e32 v9, v9
	v_rcp_f32_e32 v14, v14
	v_rcp_f32_e32 v15, v15
	v_rcp_f32_e32 v16, v16
	v_rcp_f32_e32 v17, v17
	v_pk_mul_f32 v[6:7], v[10:11], v[6:7]
	v_pk_mul_f32 v[8:9], v[12:13], v[8:9]
	v_pk_mul_f32 v[10:11], v[2:3], v[14:15]
	v_pk_mul_f32 v[12:13], v[4:5], v[16:17]
	v_cvt_pk_bf16_f32 v2, v6, v7
	v_cvt_pk_bf16_f32 v3, v8, v9
	v_cvt_pk_bf16_f32 v4, v10, v11
	v_cvt_pk_bf16_f32 v5, v12, v13
	global_store_dwordx4 v[54:55], v[2:5], off
	s_andn2_b64 exec, exec, s[2:3]
	s_cbranch_execnz .LBB0_522
	s_branch .LBB0_517
